# stacked: wave-4 batched loads, conversion counted vmcnt + batched LDS reads, LN gamma/beta loads pipelined two steps ahead with counted vmcnt
# speedup vs baseline: 1.0162x; 1.0118x over previous
; #define LAS __attribute__((address_space(3)))
; __device__ __forceinline__ unsigned pk2(float lo, float hi) { const bf16x2_t v = __builtin_convertvector((f32x2_t){lo, hi}, bf16x2_t); return __builtin_bit_cast(unsigned, v); }
; #define LDS_WAIT() asm volatile("s_waitcnt lgkmcnt(0)" ::: "memory")
; __device__ __forceinline__ void tr_store(const ItemD& d, int lane, const f32x4 (&v)[16], LAS float* scr) {
; #pragma unroll
;     for (int i = 0; i < 16; ++i) { LAS float* q = scr + (4 * i + (lane >> 4)) * 65 + (lane & 15) * 4; q[0] = v[i].x; q[1] = v[i].y; q[2] = v[i].z; q[3] = v[i].w; }
;     LDS_WAIT();
;     const int c = lane & 7;
; #pragma unroll
;     for (int j = 0; j < 8; ++j) {
;         const int n = (lane >> 3) + 8 * j; const LAS float* s = scr + (8 * c) * 65 + n;
;         u32x4 o; o.x = pk2(s[0], s[65]); o.y = pk2(s[130], s[195]); o.z = pk2(s[260], s[325]); o.w = pk2(s[390], s[455]);
.LBB0_464:
	ds_write2_b32 v173, v68, v69 offset1:1
	ds_write2_b32 v173, v70, v71 offset0:2 offset1:3
	ds_write2_b32 v174, v64, v65 offset1:1
	ds_write2_b32 v175, v66, v67 offset1:1
	ds_write2_b32 v176, v76, v77 offset1:1
	ds_write2_b32 v177, v78, v79 offset1:1
	ds_write2_b32 v178, v72, v73 offset1:1
	ds_write2_b32 v179, v74, v75 offset1:1
	ds_write2_b32 v180, v84, v85 offset1:1
	ds_write2_b32 v181, v86, v87 offset1:1
	ds_write2_b32 v182, v80, v81 offset1:1
	ds_write2_b32 v183, v82, v83 offset1:1
	ds_write2_b32 v184, v92, v93 offset1:1
	ds_write2_b32 v185, v94, v95 offset1:1
	ds_write2_b32 v186, v88, v89 offset1:1
	ds_write2_b32 v187, v90, v91 offset1:1
	ds_write2_b32 v188, v96, v97 offset1:1
	ds_write2_b32 v189, v98, v99 offset1:1
	ds_write2_b32 v190, v100, v101 offset1:1
	ds_write2_b32 v191, v102, v103 offset1:1
	ds_write2_b32 v218, v104, v105 offset1:1
	ds_write2_b32 v219, v106, v107 offset1:1
	ds_write2_b32 v220, v108, v109 offset1:1
	ds_write2_b32 v221, v110, v111 offset1:1
	ds_write2_b32 v222, v112, v113 offset1:1
	ds_write2_b32 v223, v114, v115 offset1:1
	ds_write2_b32 v224, v116, v117 offset1:1
	ds_write2_b32 v225, v118, v119 offset1:1
	ds_write2_b32 v226, v120, v121 offset1:1
	ds_write2_b32 v227, v122, v123 offset1:1
	ds_write2_b32 v228, v124, v125 offset1:1
	ds_write2_b32 v229, v126, v127 offset1:1
	s_waitcnt lgkmcnt(0)
	ds_read_b32 v64, v172
	ds_read_b32 v65, v172 offset:260
	ds_read_b32 v66, v172 offset:520
	ds_read_b32 v67, v172 offset:780
	ds_read_b32 v68, v172 offset:1040
	ds_read_b32 v69, v172 offset:1300
	ds_read_b32 v70, v172 offset:1560
	ds_read_b32 v71, v172 offset:1820
	ds_read_b32 v72, v172 offset:32
	ds_read_b32 v73, v172 offset:292
	ds_read_b32 v74, v172 offset:552
	ds_read_b32 v75, v172 offset:812
	ds_read_b32 v76, v172 offset:1072
	ds_read_b32 v77, v172 offset:1332
	ds_read_b32 v78, v172 offset:1592
	ds_read_b32 v79, v172 offset:1852
	ds_read_b32 v80, v172 offset:64
	ds_read_b32 v81, v172 offset:324
	ds_read_b32 v82, v172 offset:584
	ds_read_b32 v83, v172 offset:844
	ds_read_b32 v84, v172 offset:1104
	ds_read_b32 v85, v172 offset:1364
	ds_read_b32 v86, v172 offset:1624
	ds_read_b32 v87, v172 offset:1884
	ds_read_b32 v88, v172 offset:96
	ds_read_b32 v89, v172 offset:356
	ds_read_b32 v90, v172 offset:616
	ds_read_b32 v91, v172 offset:876
	ds_read_b32 v92, v172 offset:1136
	ds_read_b32 v93, v172 offset:1396
	ds_read_b32 v94, v172 offset:1656
	ds_read_b32 v95, v172 offset:1916
	ds_read_b32 v96, v172 offset:128
	ds_read_b32 v97, v172 offset:388
	ds_read_b32 v98, v172 offset:648
	ds_read_b32 v99, v172 offset:908
	ds_read_b32 v100, v172 offset:1168
	ds_read_b32 v101, v172 offset:1428
	ds_read_b32 v102, v172 offset:1688
	ds_read_b32 v103, v172 offset:1948
	ds_read_b32 v104, v172 offset:160
	ds_read_b32 v105, v172 offset:420
	ds_read_b32 v106, v172 offset:680
	ds_read_b32 v107, v172 offset:940
	ds_read_b32 v108, v172 offset:1200
	ds_read_b32 v109, v172 offset:1460
	ds_read_b32 v110, v172 offset:1720
	ds_read_b32 v111, v172 offset:1980
	ds_read_b32 v112, v172 offset:192
	ds_read_b32 v113, v172 offset:452
	ds_read_b32 v114, v172 offset:712
	ds_read_b32 v115, v172 offset:972
	ds_read_b32 v116, v172 offset:1232
	ds_read_b32 v117, v172 offset:1492
	ds_read_b32 v118, v172 offset:1752
	ds_read_b32 v119, v172 offset:2012
	ds_read_b32 v120, v172 offset:224
	ds_read_b32 v121, v172 offset:484
	ds_read_b32 v122, v172 offset:744
	ds_read_b32 v123, v172 offset:1004
	ds_read_b32 v124, v172 offset:1264
	ds_read_b32 v125, v172 offset:1524
	ds_read_b32 v126, v172 offset:1784
	ds_read_b32 v127, v172 offset:2044
	s_waitcnt lgkmcnt(0)
; #define LAS __attribute__((address_space(3)))
; __device__ __forceinline__ unsigned pk2(float lo, float hi) { const bf16x2_t v = __builtin_convertvector((f32x2_t){lo, hi}, bf16x2_t); return __builtin_bit_cast(unsigned, v); }
; __device__ __forceinline__ void tr_store(const ItemD& d, int lane, const f32x4 (&v)[16], LAS float* scr) {
;     ...
;     for (int j = 0; j < 8; ++j) {
;         const int n = (lane >> 3) + 8 * j; const LAS float* s = scr + (8 * c) * 65 + n;
;         u32x4 o; o.x = pk2(s[0], s[65]); o.y = pk2(s[130], s[195]); o.z = pk2(s[260], s[325]); o.w = pk2(s[390], s[455]);
;         *(u32x4*)(d.WT + (size_t)n * d.ldt + 8 * c) = o;
;     }
	v_cvt_pk_bf16_f32 v174, v64, v65
	v_cvt_pk_bf16_f32 v175, v66, v67
	v_cvt_pk_bf16_f32 v176, v68, v69
	v_mad_u64_u32 v[178:179], s[72:73], s97, v132, 0
	v_lshl_add_u64 v[168:169], s[14:15], 0, v[160:161]
	v_mov_b32_e32 v160, v179
	v_cvt_pk_bf16_f32 v177, v70, v71
	v_mad_u64_u32 v[180:181], s[72:73], s97, v131, v[160:161]
	v_mov_b32_e32 v179, v180
	v_lshl_add_u64 v[178:179], v[178:179], 1, v[168:169]
	global_store_dwordx4 v[178:179], v[174:177], off
	v_cvt_pk_bf16_f32 v65, v74, v75
	v_cvt_pk_bf16_f32 v64, v72, v73
	v_cvt_pk_bf16_f32 v66, v76, v77
	s_add_i32 s63, s63, s33
	v_cvt_pk_bf16_f32 v67, v78, v79
	v_mad_u64_u32 v[178:179], s[72:73], s97, v136, 0
	v_mov_b32_e32 v160, v179
	v_mad_u64_u32 v[180:181], s[72:73], s97, v133, v[160:161]
	v_mov_b32_e32 v179, v180
	v_lshl_add_u64 v[178:179], v[178:179], 1, v[168:169]
	global_store_dwordx4 v[178:179], v[64:67], off
	v_cvt_pk_bf16_f32 v73, v82, v83
	v_cvt_pk_bf16_f32 v72, v80, v81
	v_cvt_pk_bf16_f32 v74, v84, v85
	s_add_i32 s88, s88, s33
	v_cvt_pk_bf16_f32 v75, v86, v87
	v_mad_u64_u32 v[178:179], s[72:73], s97, v138, 0
	v_mov_b32_e32 v160, v179
	v_mad_u64_u32 v[180:181], s[72:73], s97, v135, v[160:161]
	v_mov_b32_e32 v179, v180
	v_lshl_add_u64 v[178:179], v[178:179], 1, v[168:169]
	global_store_dwordx4 v[178:179], v[72:75], off
	v_cvt_pk_bf16_f32 v81, v90, v91
	v_cvt_pk_bf16_f32 v80, v88, v89
	v_cvt_pk_bf16_f32 v82, v92, v93
	s_add_i32 s39, s39, s89
	v_cvt_pk_bf16_f32 v83, v94, v95
	v_mad_u64_u32 v[178:179], s[72:73], s97, v140, 0
	v_mov_b32_e32 v160, v179
	v_mad_u64_u32 v[180:181], s[72:73], s97, v137, v[160:161]
	v_mov_b32_e32 v179, v180
	v_lshl_add_u64 v[178:179], v[178:179], 1, v[168:169]
	global_store_dwordx4 v[178:179], v[80:83], off
	v_cvt_pk_bf16_f32 v89, v98, v99
	v_cvt_pk_bf16_f32 v88, v96, v97
	v_cvt_pk_bf16_f32 v90, v100, v101
	s_add_i32 s94, s94, s22
	v_cvt_pk_bf16_f32 v91, v102, v103
	v_mad_u64_u32 v[178:179], s[72:73], s97, v142, 0
	v_mov_b32_e32 v160, v179
	v_mad_u64_u32 v[180:181], s[72:73], s97, v139, v[160:161]
	v_mov_b32_e32 v179, v180
	v_lshl_add_u64 v[178:179], v[178:179], 1, v[168:169]
	global_store_dwordx4 v[178:179], v[88:91], off
	v_cvt_pk_bf16_f32 v97, v106, v107
	v_cvt_pk_bf16_f32 v96, v104, v105
	v_cvt_pk_bf16_f32 v98, v108, v109
	s_add_i32 s23, s23, s33
	v_cvt_pk_bf16_f32 v99, v110, v111
	v_mad_u64_u32 v[178:179], s[72:73], s97, v162, 0
	v_mov_b32_e32 v160, v179
	v_mad_u64_u32 v[180:181], s[72:73], s97, v141, v[160:161]
	v_mov_b32_e32 v179, v180
	v_lshl_add_u64 v[178:179], v[178:179], 1, v[168:169]
	global_store_dwordx4 v[178:179], v[96:99], off
	v_cvt_pk_bf16_f32 v105, v114, v115
	v_cvt_pk_bf16_f32 v104, v112, v113
	v_cvt_pk_bf16_f32 v106, v116, v117
	s_add_i32 s35, s35, s89
	v_cvt_pk_bf16_f32 v107, v118, v119
	v_mad_u64_u32 v[178:179], s[72:73], s97, v164, 0
	v_mov_b32_e32 v160, v179
	v_mad_u64_u32 v[180:181], s[72:73], s97, v143, v[160:161]
	v_mov_b32_e32 v179, v180
	v_lshl_add_u64 v[178:179], v[178:179], 1, v[168:169]
	global_store_dwordx4 v[178:179], v[104:107], off
	v_cvt_pk_bf16_f32 v113, v122, v123
	v_cvt_pk_bf16_f32 v112, v120, v121
	v_cvt_pk_bf16_f32 v114, v124, v125
	s_add_i32 s12, s84, s63
	v_cvt_pk_bf16_f32 v115, v126, v127
	v_mad_u64_u32 v[178:179], s[72:73], s97, v166, 0
	v_mov_b32_e32 v160, v179
	v_mad_u64_u32 v[180:181], s[72:73], s97, v163, v[160:161]
	v_mov_b32_e32 v179, v180
	v_lshl_add_u64 v[168:169], v[178:179], 1, v[168:169]
	global_store_dwordx4 v[168:169], v[112:115], off
	s_waitcnt lgkmcnt(0)
	s_cmp_gt_i32 s12, 0xb1ff
	s_cselect_b64 s[74:75], -1, 0

; #define LAS __attribute__((address_space(3)))
; __device__ __forceinline__ unsigned pk2(float lo, float hi) { const bf16x2_t v = __builtin_convertvector((f32x2_t){lo, hi}, bf16x2_t); return __builtin_bit_cast(unsigned, v); }
; #define LDS_WAIT() asm volatile("s_waitcnt lgkmcnt(0)" ::: "memory")
; __device__ __forceinline__ void tr_store(const ItemD& d, int lane, const f32x4 (&v)[16], LAS float* scr) {
; #pragma unroll
;     for (int i = 0; i < 16; ++i) { LAS float* q = scr + (4 * i + (lane >> 4)) * 65 + (lane & 15) * 4; q[0] = v[i].x; q[1] = v[i].y; q[2] = v[i].z; q[3] = v[i].w; }
;     LDS_WAIT();
;     const int c = lane & 7;
; #pragma unroll
;     for (int j = 0; j < 8; ++j) {
;         const int n = (lane >> 3) + 8 * j; const LAS float* s = scr + (8 * c) * 65 + n;
;         u32x4 o; o.x = pk2(s[0], s[65]); o.y = pk2(s[130], s[195]); o.z = pk2(s[260], s[325]); o.w = pk2(s[390], s[455]);
.LBB0_483:
	v_add_u32_e32 v174, 0x410, v173
	v_add_u32_e32 v175, 0x418, v173
	v_add_u32_e32 v176, 0x820, v173
	v_add_u32_e32 v177, 0x828, v173
	v_add_u32_e32 v178, 0xc30, v173
	v_add_u32_e32 v179, 0xc38, v173
	v_add_u32_e32 v180, 0x1040, v173
	v_add_u32_e32 v181, 0x1048, v173
	v_add_u32_e32 v182, 0x1450, v173
	v_add_u32_e32 v183, 0x1458, v173
	v_add_u32_e32 v184, 0x1860, v173
	v_add_u32_e32 v185, 0x1868, v173
	v_add_u32_e32 v186, 0x1c70, v173
	v_add_u32_e32 v187, 0x1c78, v173
	v_add_u32_e32 v188, 0x2080, v173
	v_add_u32_e32 v189, 0x2088, v173
	v_add_u32_e32 v190, 0x2490, v173
	v_add_u32_e32 v191, 0x2498, v173
	v_add_u32_e32 v218, 0x28a0, v173
	v_add_u32_e32 v219, 0x28a8, v173
	v_add_u32_e32 v220, 0x2cb0, v173
	v_add_u32_e32 v221, 0x2cb8, v173
	v_add_u32_e32 v222, 0x30c0, v173
	v_add_u32_e32 v223, 0x30c8, v173
	v_add_u32_e32 v224, 0x34d0, v173
	v_add_u32_e32 v225, 0x34d8, v173
	v_add_u32_e32 v226, 0x38e0, v173
	v_add_u32_e32 v227, 0x38e8, v173
	v_add_u32_e32 v228, 0x3cf0, v173
	v_add_u32_e32 v229, 0x3cf8, v173
	s_waitcnt lgkmcnt(0)
	ds_write2_b32 v173, v0, v1 offset1:1
	ds_write2_b32 v173, v2, v3 offset0:2 offset1:3
	ds_write2_b32 v174, v4, v5 offset1:1
	ds_write2_b32 v175, v6, v7 offset1:1
	ds_write2_b32 v176, v8, v9 offset1:1
	ds_write2_b32 v177, v10, v11 offset1:1
	ds_write2_b32 v178, v12, v13 offset1:1
	ds_write2_b32 v179, v14, v15 offset1:1
	ds_write2_b32 v180, v16, v17 offset1:1
	ds_write2_b32 v181, v18, v19 offset1:1
	ds_write2_b32 v182, v20, v21 offset1:1
	ds_write2_b32 v183, v22, v23 offset1:1
	ds_write2_b32 v184, v24, v25 offset1:1
	ds_write2_b32 v185, v26, v27 offset1:1
	ds_write2_b32 v186, v28, v29 offset1:1
	ds_write2_b32 v187, v30, v31 offset1:1
	ds_write2_b32 v188, v32, v33 offset1:1
	ds_write2_b32 v189, v34, v35 offset1:1
	ds_write2_b32 v190, v36, v37 offset1:1
	ds_write2_b32 v191, v38, v39 offset1:1
	ds_write2_b32 v218, v40, v41 offset1:1
	ds_write2_b32 v219, v42, v43 offset1:1
	ds_write2_b32 v220, v44, v45 offset1:1
	ds_write2_b32 v221, v46, v47 offset1:1
	ds_write2_b32 v222, v48, v49 offset1:1
	ds_write2_b32 v223, v50, v51 offset1:1
	ds_write2_b32 v224, v52, v53 offset1:1
	ds_write2_b32 v225, v54, v55 offset1:1
	ds_write2_b32 v226, v56, v57 offset1:1
	ds_write2_b32 v227, v58, v59 offset1:1
	ds_write2_b32 v228, v60, v61 offset1:1
	ds_write2_b32 v229, v62, v63 offset1:1
	s_waitcnt lgkmcnt(0)
	ds_read_b32 v0, v172
	ds_read_b32 v1, v172 offset:260
	ds_read_b32 v2, v172 offset:520
	ds_read_b32 v3, v172 offset:780
	ds_read_b32 v4, v172 offset:1040
	ds_read_b32 v5, v172 offset:1300
	ds_read_b32 v6, v172 offset:1560
	ds_read_b32 v7, v172 offset:1820
	ds_read_b32 v8, v172 offset:32
	ds_read_b32 v9, v172 offset:292
	ds_read_b32 v10, v172 offset:552
	ds_read_b32 v11, v172 offset:812
	ds_read_b32 v12, v172 offset:1072
	ds_read_b32 v13, v172 offset:1332
	ds_read_b32 v14, v172 offset:1592
	ds_read_b32 v15, v172 offset:1852
	ds_read_b32 v16, v172 offset:64
	ds_read_b32 v17, v172 offset:324
	ds_read_b32 v18, v172 offset:584
	ds_read_b32 v19, v172 offset:844
	ds_read_b32 v20, v172 offset:1104
	ds_read_b32 v21, v172 offset:1364
	ds_read_b32 v22, v172 offset:1624
	ds_read_b32 v23, v172 offset:1884
	ds_read_b32 v24, v172 offset:96
	ds_read_b32 v25, v172 offset:356
	ds_read_b32 v26, v172 offset:616
	ds_read_b32 v27, v172 offset:876
	ds_read_b32 v28, v172 offset:1136
	ds_read_b32 v29, v172 offset:1396
	ds_read_b32 v30, v172 offset:1656
	ds_read_b32 v31, v172 offset:1916
	ds_read_b32 v32, v172 offset:128
	ds_read_b32 v33, v172 offset:388
	ds_read_b32 v34, v172 offset:648
	ds_read_b32 v35, v172 offset:908
	ds_read_b32 v36, v172 offset:1168
	ds_read_b32 v37, v172 offset:1428
	ds_read_b32 v38, v172 offset:1688
	ds_read_b32 v39, v172 offset:1948
	ds_read_b32 v40, v172 offset:160
	ds_read_b32 v41, v172 offset:420
	ds_read_b32 v42, v172 offset:680
	ds_read_b32 v43, v172 offset:940
	ds_read_b32 v44, v172 offset:1200
	ds_read_b32 v45, v172 offset:1460
	ds_read_b32 v46, v172 offset:1720
	ds_read_b32 v47, v172 offset:1980
	ds_read_b32 v48, v172 offset:192
	ds_read_b32 v49, v172 offset:452
	ds_read_b32 v50, v172 offset:712
	ds_read_b32 v51, v172 offset:972
	ds_read_b32 v52, v172 offset:1232
	ds_read_b32 v53, v172 offset:1492
	ds_read_b32 v54, v172 offset:1752
	ds_read_b32 v55, v172 offset:2012
	ds_read_b32 v56, v172 offset:224
	ds_read_b32 v57, v172 offset:484
	ds_read_b32 v58, v172 offset:744
	ds_read_b32 v59, v172 offset:1004
	ds_read_b32 v60, v172 offset:1264
	ds_read_b32 v61, v172 offset:1524
	ds_read_b32 v62, v172 offset:1784
	ds_read_b32 v63, v172 offset:2044
	s_waitcnt lgkmcnt(0)
; #define LAS __attribute__((address_space(3)))
; #define KIN(i) ((const float*)karg(i))
; __device__ __forceinline__ unsigned pk2(float lo, float hi) { const bf16x2_t v = __builtin_convertvector((f32x2_t){lo, hi}, bf16x2_t); return __builtin_bit_cast(unsigned, v); }
; #define LDS_WAIT() asm volatile("s_waitcnt lgkmcnt(0)" ::: "memory")
; __device__ __forceinline__ void tr_store(const ItemD& d, int lane, const f32x4 (&v)[16], LAS float* scr) {
;     ...
;     for (int j = 0; j < 8; ++j) {
;         const int n = (lane >> 3) + 8 * j; const LAS float* s = scr + (8 * c) * 65 + n;
;         u32x4 o; o.x = pk2(s[0], s[65]); o.y = pk2(s[130], s[195]); o.z = pk2(s[260], s[325]); o.w = pk2(s[390], s[455]);
;         *(u32x4*)(d.WT + (size_t)n * d.ldt + 8 * c) = o;
;     }
;     LDS_WAIT();
; }
; __device__ __forceinline__ ItemD decode_item(int it) {
;     unsigned char* ws = KWS;
;     int r = it;
;     if (r < I_IN) { const int kb = r >> 7, nb = r & 127, n0 = nb * 64, seg = n0 >> 11; const int dseg = seg == 2 ? 3 : (seg == 3 ? 2 : seg);
;         return mk_item(KIN(5), 8192, kb * 64, n0, (bf16_t*)(ws + WS_WIN), DM, dseg * 2048 + (n0 & 2047)); }
;     r -= I_IN;
;     if (r < I_OUT) { const int kb = r >> 6, nb = r & 63; return mk_item(KIN(9), DM, kb * 64, nb * 64, (bf16_t*)(ws + WS_WOUT), DM, nb * 64); }
;     r -= I_OUT;
;     if (r < 2 * I_G) { const int up = r >= I_G; if (up) r -= I_G; const int kb = r / 172, nb = r % 172, n0 = nb * 64;
;         return mk_item(KIN(up ? 13 : 12), DFF, kb * 64, n0, (bf16_t*)(ws + WS_WGU), DM, (n0 >> 7) * 256 + (n0 & 127) + (up ? 128 : 0)); }
;     r -= 2 * I_G;
;     if (r < I_DN) { const int kb = r >> 6, nb = r & 63; return mk_item(KIN(14), DM, kb * 64, nb * 64, (bf16_t*)(ws + WS_WDOWN), DFF, nb * 64); }
;     r -= I_DN;
;     { const int g = r >> 6, rr = r & 63, kb = rr >> 3, nb = rr & 7;
;       return mk_item(KIN(7) + (size_t)g * 512 * 512, 512, kb * 64, nb * 64, (bf16_t*)(ws + WS_WPOOL) + (size_t)g * 512 * 512, 512, nb * 64); }
	v_lshlrev_b32_e32 v160, 1, v134
	v_lshl_add_u64 v[168:169], s[10:11], 0, v[160:161]
	s_andn2_b64 vcc, exec, s[72:73]
	v_cvt_pk_bf16_f32 v230, v0, v1
	v_cvt_pk_bf16_f32 v231, v2, v3
	v_cvt_pk_bf16_f32 v232, v4, v5
	v_cvt_pk_bf16_f32 v233, v6, v7
	v_mad_u64_u32 v[234:235], s[74:75], s5, v132, 0
	v_mov_b32_e32 v236, v235
	v_mad_u64_u32 v[236:237], s[74:75], s5, v131, v[236:237]
	v_mov_b32_e32 v235, v236
	v_lshl_add_u64 v[234:235], v[234:235], 1, v[168:169]
	global_store_dwordx4 v[234:235], v[230:233], off
	v_cvt_pk_bf16_f32 v0, v8, v9
	v_cvt_pk_bf16_f32 v1, v10, v11
	v_cvt_pk_bf16_f32 v2, v12, v13
	v_cvt_pk_bf16_f32 v3, v14, v15
	v_mad_u64_u32 v[234:235], s[74:75], s5, v136, 0
	v_mov_b32_e32 v236, v235
	v_mad_u64_u32 v[236:237], s[74:75], s5, v133, v[236:237]
	v_mov_b32_e32 v235, v236
	v_lshl_add_u64 v[234:235], v[234:235], 1, v[168:169]
	global_store_dwordx4 v[234:235], v[0:3], off
	v_cvt_pk_bf16_f32 v8, v16, v17
	v_cvt_pk_bf16_f32 v9, v18, v19
	v_cvt_pk_bf16_f32 v10, v20, v21
	v_cvt_pk_bf16_f32 v11, v22, v23
	v_mad_u64_u32 v[234:235], s[74:75], s5, v138, 0
	v_mov_b32_e32 v236, v235
	v_mad_u64_u32 v[236:237], s[74:75], s5, v135, v[236:237]
	v_mov_b32_e32 v235, v236
	v_lshl_add_u64 v[234:235], v[234:235], 1, v[168:169]
	global_store_dwordx4 v[234:235], v[8:11], off
	v_cvt_pk_bf16_f32 v16, v24, v25
	v_cvt_pk_bf16_f32 v17, v26, v27
	v_cvt_pk_bf16_f32 v18, v28, v29
	v_cvt_pk_bf16_f32 v19, v30, v31
	v_mad_u64_u32 v[234:235], s[74:75], s5, v140, 0
	v_mov_b32_e32 v236, v235
	v_mad_u64_u32 v[236:237], s[74:75], s5, v137, v[236:237]
	v_mov_b32_e32 v235, v236
	v_lshl_add_u64 v[234:235], v[234:235], 1, v[168:169]
	global_store_dwordx4 v[234:235], v[16:19], off
	v_cvt_pk_bf16_f32 v24, v32, v33
	v_cvt_pk_bf16_f32 v25, v34, v35
	v_cvt_pk_bf16_f32 v26, v36, v37
	v_cvt_pk_bf16_f32 v27, v38, v39
	v_mad_u64_u32 v[234:235], s[74:75], s5, v142, 0
	v_mov_b32_e32 v236, v235
	v_mad_u64_u32 v[236:237], s[74:75], s5, v139, v[236:237]
	v_mov_b32_e32 v235, v236
	v_lshl_add_u64 v[234:235], v[234:235], 1, v[168:169]
	global_store_dwordx4 v[234:235], v[24:27], off
	v_cvt_pk_bf16_f32 v32, v40, v41
	v_cvt_pk_bf16_f32 v33, v42, v43
	v_cvt_pk_bf16_f32 v34, v44, v45
	v_cvt_pk_bf16_f32 v35, v46, v47
	v_mad_u64_u32 v[234:235], s[74:75], s5, v162, 0
	v_mov_b32_e32 v236, v235
	v_mad_u64_u32 v[236:237], s[74:75], s5, v141, v[236:237]
	v_mov_b32_e32 v235, v236
	v_lshl_add_u64 v[234:235], v[234:235], 1, v[168:169]
	global_store_dwordx4 v[234:235], v[32:35], off
	v_cvt_pk_bf16_f32 v40, v48, v49
	v_cvt_pk_bf16_f32 v41, v50, v51
	v_cvt_pk_bf16_f32 v42, v52, v53
	v_cvt_pk_bf16_f32 v43, v54, v55
	v_mad_u64_u32 v[234:235], s[74:75], s5, v164, 0
	v_mov_b32_e32 v236, v235
	v_mad_u64_u32 v[236:237], s[74:75], s5, v143, v[236:237]
	v_mov_b32_e32 v235, v236
	v_lshl_add_u64 v[234:235], v[234:235], 1, v[168:169]
	global_store_dwordx4 v[234:235], v[40:43], off
	v_cvt_pk_bf16_f32 v48, v56, v57
	v_cvt_pk_bf16_f32 v49, v58, v59
	v_cvt_pk_bf16_f32 v50, v60, v61
	v_cvt_pk_bf16_f32 v51, v62, v63
	v_mad_u64_u32 v[234:235], s[74:75], s5, v166, 0
	v_mov_b32_e32 v236, v235
	v_mad_u64_u32 v[236:237], s[74:75], s5, v163, v[236:237]
	v_mov_b32_e32 v235, v236
	v_lshl_add_u64 v[168:169], v[234:235], 1, v[168:169]
	global_store_dwordx4 v[168:169], v[48:51], off
	s_waitcnt lgkmcnt(0)
	s_mov_b64 s[74:75], -1
	s_cbranch_vccnz .LBB0_465
	s_add_i32 s12, s84, s88
	s_add_i32 s82, s12, 0x1ffb
	s_cmp_gt_i32 s82, 0xb1ff
	s_cbranch_scc1 .Lcv2_skipA
	s_load_dwordx2 s[10:11], s[0:1], 0x90
	s_cmpk_gt_i32 s82, 0x1fff
	s_mov_b64 s[80:81], -1
	s_cbranch_scc0 .LBB0_499
	s_cmpk_gt_u32 s82, 0x2fff
	s_cbranch_scc0 .LBB0_496
	s_cmpk_gt_u32 s82, 0x85ff
	s_cbranch_scc0 .LBB0_493
	s_cmpk_gt_u32 s82, 0xb0ff
	s_mov_b64 s[78:79], -1
	s_cbranch_scc0 .LBB0_490
	s_load_dwordx2 s[72:73], s[0:1], 0x38
	s_add_i32 s12, s12, 0xffff6efb
	s_lshr_b32 s12, s12, 6
	s_lshl_b64 s[74:75], s[12:13], 20
	v_readlane_b32 s47, v250, 13
	s_waitcnt lgkmcnt(0)
	s_add_u32 s5, s72, s74
	s_addc_u32 s74, s73, s75
	s_add_i32 s72, s47, s39
	s_and_b32 s76, s72, 0x1c0
	s_add_i32 s72, s22, s94
	s_and_b32 s78, s72, 0x1c0
	s_lshl_b64 s[72:73], s[12:13], 19
	s_add_u32 s12, s10, s72
	s_addc_u32 s73, s11, s73
	s_add_u32 s72, s12, 0x12200000
	s_addc_u32 s73, s73, 0
	s_lshl_b32 s12, s76, 11
	s_add_u32 s5, s5, s12
	s_addc_u32 s12, s74, 0
	s_lshl_b32 s74, s78, 2
	s_add_u32 s74, s5, s74
	s_mov_b32 s77, s13
	s_addc_u32 s75, s12, 0
	s_lshl_b32 s12, s78, 9
	s_mov_b64 s[78:79], 0

; __device__ __forceinline__ void bf8_unpack(const u32x4 x, float (&f)[8]) { f[0] = bf_lo(x.x); f[1] = bf_hi(x.x); f[2] = bf_lo(x.y); f[3] = bf_hi(x.y); f[4] = bf_lo(x.z); f[5] = bf_hi(x.z); f[6] = bf_lo(x.w); f[7] = bf_hi(x.w); }
; template <bool FINAL>
; __device__ __forceinline__ void ln_phase(const bf16_t* pre, const float* gam, const float* bet, float* outf, bf16_t* outb, int wave) {
;     ...
;     for (int row = gw; row < NTOK; row += NGW) {
;         const u32x4* src = (const u32x4*)(pre + (size_t)row * DM) + lane;
;         float v[8][8]; float s = 0.f;
; #pragma unroll
;         for (int j = 0; j < 8; ++j) { const u32x4 x = src[64 * j]; bf8_unpack(x, v[j]);
; #pragma unroll
;             for (int e = 0; e < 8; ++e) s += v[j][e]; }
; #pragma unroll
;         for (int o = 1; o < 64; o <<= 1) s += __shfl_xor(s, o);
;         const float mean = s * (1.0f / DM); float q = 0.f;
;     ...
;         for (int j = 0; j < 8; ++j) {
;             const int c0 = 8 * (lane + 64 * j);
;             const f32x4 g0 = *(const f32x4*)(gam + c0), g1 = *(const f32x4*)(gam + c0 + 4), b0 = *(const f32x4*)(bet + c0), b1 = *(const f32x4*)(bet + c0 + 4);
.LBB0_1019:
	v_lshl_add_u64 v[58:59], s[8:9], 0, v[54:55]
	v_add_co_u32_e32 v76, vcc, 0x24b00000, v58
	global_load_dwordx4 v[4:7], v[16:17], off
	global_load_dwordx4 v[0:3], v[16:17], off offset:16
	global_load_dwordx4 v[12:15], v[18:19], off
	global_load_dwordx4 v[8:11], v[18:19], off offset:16
	v_addc_co_u32_e32 v77, vcc, 0, v59, vcc
	v_add_co_u32_e32 v58, vcc, s3, v58
	global_load_dwordx4 v[60:63], v[76:77], off
	global_load_dwordx4 v[64:67], v[76:77], off offset:1024
	global_load_dwordx4 v[68:71], v[76:77], off offset:2048
	global_load_dwordx4 v[72:75], v[76:77], off offset:3072
	v_addc_co_u32_e32 v59, vcc, 0, v59, vcc
	global_load_dwordx4 v[76:79], v[58:59], off offset:3072
	global_load_dwordx4 v[80:83], v[58:59], off
	global_load_dwordx4 v[84:87], v[58:59], off offset:1024
	global_load_dwordx4 v[100:103], v[58:59], off offset:2048
	v_lshl_add_u64 v[56:57], s[8:9], 0, v[52:53]
	v_add_co_u32_e64 v56, s[6:7], s5, v56
	s_add_i32 s12, s12, s40
	s_nop 0
	v_addc_co_u32_e64 v57, s[6:7], 0, v57, s[6:7]
	global_load_dwordx4 v[200:203], v[18:19], off offset:2048
	global_load_dwordx4 v[204:207], v[16:17], off offset:2048
	global_load_dwordx4 v[208:211], v[16:17], off offset:2064
	global_load_dwordx4 v[212:215], v[18:19], off offset:2064
	s_waitcnt vmcnt(0) lgkmcnt(0)
	v_lshlrev_b32_e32 v88, 16, v60
	v_and_b32_e32 v89, 0xffff0000, v60
	v_add_f32_e32 v90, 0, v88
	v_lshlrev_b32_e32 v60, 16, v61
	v_lshlrev_b32_e32 v136, 16, v76
	v_and_b32_e32 v137, 0xffff0000, v76
	v_add_f32_e32 v76, v90, v89
	v_and_b32_e32 v61, 0xffff0000, v61
	v_add_f32_e32 v76, v76, v60
	v_lshlrev_b32_e32 v58, 16, v62
	v_add_f32_e32 v76, v76, v61
	v_and_b32_e32 v59, 0xffff0000, v62
	v_add_f32_e32 v76, v76, v58
	v_lshlrev_b32_e32 v62, 16, v63
	v_add_f32_e32 v76, v76, v59
	v_and_b32_e32 v63, 0xffff0000, v63
	v_add_f32_e32 v76, v76, v62
	v_lshlrev_b32_e32 v106, 16, v64
	v_add_f32_e32 v76, v76, v63
	v_and_b32_e32 v107, 0xffff0000, v64
	v_add_f32_e32 v76, v76, v106
	v_lshlrev_b32_e32 v64, 16, v65
	v_add_f32_e32 v76, v76, v107
	v_and_b32_e32 v65, 0xffff0000, v65
	v_add_f32_e32 v76, v76, v64
	v_lshlrev_b32_e32 v104, 16, v66
	v_add_f32_e32 v76, v76, v65
	v_and_b32_e32 v105, 0xffff0000, v66
	v_add_f32_e32 v76, v76, v104
	v_lshlrev_b32_e32 v66, 16, v67
	v_add_f32_e32 v76, v76, v105
	v_and_b32_e32 v67, 0xffff0000, v67
	v_add_f32_e32 v76, v76, v66
	v_lshlrev_b32_e32 v110, 16, v68
	v_add_f32_e32 v76, v76, v67
	v_and_b32_e32 v111, 0xffff0000, v68
	v_add_f32_e32 v76, v76, v110
	v_lshlrev_b32_e32 v68, 16, v69
	v_add_f32_e32 v76, v76, v111
	v_and_b32_e32 v69, 0xffff0000, v69
	v_add_f32_e32 v76, v76, v68
	v_lshlrev_b32_e32 v108, 16, v70
	v_add_f32_e32 v76, v76, v69
	v_and_b32_e32 v109, 0xffff0000, v70
	v_add_f32_e32 v76, v76, v108
	v_lshlrev_b32_e32 v70, 16, v71
	v_add_f32_e32 v76, v76, v109
	v_and_b32_e32 v71, 0xffff0000, v71
	v_add_f32_e32 v76, v76, v70
	v_lshlrev_b32_e32 v114, 16, v72
	v_add_f32_e32 v76, v76, v71
	v_and_b32_e32 v115, 0xffff0000, v72
	v_add_f32_e32 v76, v76, v114
	v_lshlrev_b32_e32 v72, 16, v73
	v_add_f32_e32 v76, v76, v115
	v_and_b32_e32 v73, 0xffff0000, v73
	v_add_f32_e32 v76, v76, v72
	v_lshlrev_b32_e32 v112, 16, v74
	v_add_f32_e32 v76, v76, v73
	v_and_b32_e32 v113, 0xffff0000, v74
	v_add_f32_e32 v76, v76, v112
	v_lshlrev_b32_e32 v74, 16, v75
	v_add_f32_e32 v76, v76, v113
	v_and_b32_e32 v75, 0xffff0000, v75
	v_add_f32_e32 v76, v76, v74
	v_lshlrev_b32_e32 v118, 16, v82
	v_and_b32_e32 v119, 0xffff0000, v82
	v_lshlrev_b32_e32 v82, 16, v80
	v_add_f32_e32 v76, v76, v75
	v_lshlrev_b32_e32 v120, 16, v83
	v_and_b32_e32 v121, 0xffff0000, v83
	v_and_b32_e32 v83, 0xffff0000, v80
	v_add_f32_e32 v76, v76, v82
	v_lshlrev_b32_e32 v80, 16, v81
	v_add_f32_e32 v76, v76, v83
	v_and_b32_e32 v81, 0xffff0000, v81
	v_add_f32_e32 v76, v76, v80
	v_add_f32_e32 v76, v76, v81
	v_add_f32_e32 v76, v76, v118
	v_add_f32_e32 v76, v76, v119
	v_add_f32_e32 v76, v76, v120
	v_lshlrev_b32_e32 v126, 16, v84
	v_add_f32_e32 v76, v76, v121
	v_and_b32_e32 v127, 0xffff0000, v84
	v_add_f32_e32 v76, v76, v126
	v_lshlrev_b32_e32 v128, 16, v85
	v_add_f32_e32 v76, v76, v127
	v_and_b32_e32 v129, 0xffff0000, v85
	v_add_f32_e32 v76, v76, v128
	v_lshlrev_b32_e32 v122, 16, v86
	v_add_f32_e32 v76, v76, v129
	v_and_b32_e32 v123, 0xffff0000, v86
	v_add_f32_e32 v76, v76, v122
	v_lshlrev_b32_e32 v124, 16, v87
	v_add_f32_e32 v76, v76, v123
	v_and_b32_e32 v125, 0xffff0000, v87
	v_add_f32_e32 v76, v76, v124
	v_lshlrev_b32_e32 v132, 16, v100
	v_add_f32_e32 v76, v76, v125
	v_and_b32_e32 v133, 0xffff0000, v100
	v_add_f32_e32 v76, v76, v132
	v_lshlrev_b32_e32 v100, 16, v101
	v_add_f32_e32 v76, v76, v133
	v_and_b32_e32 v101, 0xffff0000, v101
	v_add_f32_e32 v76, v76, v100
	v_lshlrev_b32_e32 v130, 16, v102
	v_add_f32_e32 v76, v76, v101
	v_and_b32_e32 v131, 0xffff0000, v102
	v_add_f32_e32 v76, v76, v130
	v_lshlrev_b32_e32 v102, 16, v103
	v_add_f32_e32 v76, v76, v131
	v_and_b32_e32 v103, 0xffff0000, v103
	v_add_f32_e32 v76, v76, v102
	v_add_f32_e32 v76, v76, v103
	v_add_f32_e32 v76, v76, v136
	v_lshlrev_b32_e32 v138, 16, v77
	v_add_f32_e32 v76, v76, v137
	v_and_b32_e32 v139, 0xffff0000, v77
	v_add_f32_e32 v76, v76, v138
	v_lshlrev_b32_e32 v134, 16, v78
	v_add_f32_e32 v76, v76, v139
	v_and_b32_e32 v135, 0xffff0000, v78
	v_add_f32_e32 v76, v76, v134
	v_lshlrev_b32_e32 v117, 16, v79
	v_add_f32_e32 v76, v76, v135
	v_and_b32_e32 v116, 0xffff0000, v79
	v_add_f32_e32 v76, v76, v117
	v_add_f32_e32 v76, v76, v116
	ds_bpermute_b32 v77, v91, v76
	s_waitcnt lgkmcnt(0)
	v_add_f32_e32 v76, v76, v77
	ds_bpermute_b32 v77, v92, v76
	s_waitcnt lgkmcnt(0)
	v_add_f32_e32 v76, v76, v77
	ds_bpermute_b32 v77, v93, v76
	s_waitcnt lgkmcnt(0)
; template <bool FINAL>
; __device__ __forceinline__ void ln_phase(const bf16_t* pre, const float* gam, const float* bet, float* outf, bf16_t* outb, int wave) {
;     ...
;         for (int o = 1; o < 64; o <<= 1) s += __shfl_xor(s, o);
;         const float mean = s * (1.0f / DM); float q = 0.f;
; #pragma unroll
;         for (int j = 0; j < 8; ++j)
; #pragma unroll
;             for (int e = 0; e < 8; ++e) { v[j][e] -= mean; q += v[j][e] * v[j][e]; }
; #pragma unroll
;         for (int o = 1; o < 64; o <<= 1) q += __shfl_xor(q, o);
	v_add_f32_e32 v76, v76, v77
	ds_bpermute_b32 v77, v94, v76
	s_waitcnt lgkmcnt(0)
	v_add_f32_e32 v76, v76, v77
	ds_bpermute_b32 v77, v95, v76
	s_waitcnt lgkmcnt(0)
	v_add_f32_e32 v76, v76, v77
	ds_bpermute_b32 v77, v96, v76
	s_waitcnt lgkmcnt(0)
	v_add_f32_e32 v76, v76, v77
	v_mul_f32_e32 v90, 0x39800000, v76
	v_pk_add_f32 v[140:141], v[88:89], v[90:91] op_sel_hi:[1,0] neg_lo:[0,1] neg_hi:[0,1]
	v_pk_add_f32 v[142:143], v[60:61], v[90:91] op_sel_hi:[1,0] neg_lo:[0,1] neg_hi:[0,1]
	v_pk_add_f32 v[152:153], v[68:69], v[90:91] op_sel_hi:[1,0] neg_lo:[0,1] neg_hi:[0,1]
	v_pk_add_f32 v[68:69], v[100:101], v[90:91] op_sel_hi:[1,0] neg_lo:[0,1] neg_hi:[0,1]
	v_pk_mul_f32 v[100:101], v[140:141], v[140:141]
	v_pk_add_f32 v[144:145], v[58:59], v[90:91] op_sel_hi:[1,0] neg_lo:[0,1] neg_hi:[0,1]
	v_pk_add_f32 v[146:147], v[62:63], v[90:91] op_sel_hi:[1,0] neg_lo:[0,1] neg_hi:[0,1]
	v_pk_add_f32 v[106:107], v[106:107], v[90:91] op_sel_hi:[1,0] neg_lo:[0,1] neg_hi:[0,1]
	v_pk_add_f32 v[148:149], v[64:65], v[90:91] op_sel_hi:[1,0] neg_lo:[0,1] neg_hi:[0,1]
	v_pk_add_f32 v[104:105], v[104:105], v[90:91] op_sel_hi:[1,0] neg_lo:[0,1] neg_hi:[0,1]
	v_pk_add_f32 v[150:151], v[66:67], v[90:91] op_sel_hi:[1,0] neg_lo:[0,1] neg_hi:[0,1]
	v_pk_add_f32 v[110:111], v[110:111], v[90:91] op_sel_hi:[1,0] neg_lo:[0,1] neg_hi:[0,1]
	v_pk_add_f32 v[108:109], v[108:109], v[90:91] op_sel_hi:[1,0] neg_lo:[0,1] neg_hi:[0,1]
	v_pk_add_f32 v[154:155], v[70:71], v[90:91] op_sel_hi:[1,0] neg_lo:[0,1] neg_hi:[0,1]
	v_pk_add_f32 v[114:115], v[114:115], v[90:91] op_sel_hi:[1,0] neg_lo:[0,1] neg_hi:[0,1]
	v_pk_add_f32 v[156:157], v[72:73], v[90:91] op_sel_hi:[1,0] neg_lo:[0,1] neg_hi:[0,1]
	v_pk_add_f32 v[112:113], v[112:113], v[90:91] op_sel_hi:[1,0] neg_lo:[0,1] neg_hi:[0,1]
	v_pk_add_f32 v[158:159], v[74:75], v[90:91] op_sel_hi:[1,0] neg_lo:[0,1] neg_hi:[0,1]
	v_pk_add_f32 v[82:83], v[82:83], v[90:91] op_sel_hi:[1,0] neg_lo:[0,1] neg_hi:[0,1]
	v_pk_add_f32 v[84:85], v[80:81], v[90:91] op_sel_hi:[1,0] neg_lo:[0,1] neg_hi:[0,1]
	v_pk_add_f32 v[86:87], v[118:119], v[90:91] op_sel_hi:[1,0] neg_lo:[0,1] neg_hi:[0,1]
	v_pk_add_f32 v[88:89], v[120:121], v[90:91] op_sel_hi:[1,0] neg_lo:[0,1] neg_hi:[0,1]
	v_pk_add_f32 v[74:75], v[126:127], v[90:91] op_sel_hi:[1,0] neg_lo:[0,1] neg_hi:[0,1]
	v_pk_add_f32 v[76:77], v[128:129], v[90:91] op_sel_hi:[1,0] neg_lo:[0,1] neg_hi:[0,1]
	v_pk_add_f32 v[78:79], v[122:123], v[90:91] op_sel_hi:[1,0] neg_lo:[0,1] neg_hi:[0,1]
	v_pk_add_f32 v[80:81], v[124:125], v[90:91] op_sel_hi:[1,0] neg_lo:[0,1] neg_hi:[0,1]
	v_pk_add_f32 v[66:67], v[132:133], v[90:91] op_sel_hi:[1,0] neg_lo:[0,1] neg_hi:[0,1]
	v_pk_add_f32 v[70:71], v[130:131], v[90:91] op_sel_hi:[1,0] neg_lo:[0,1] neg_hi:[0,1]
	v_pk_add_f32 v[72:73], v[102:103], v[90:91] op_sel_hi:[1,0] neg_lo:[0,1] neg_hi:[0,1]
	v_pk_add_f32 v[58:59], v[136:137], v[90:91] op_sel_hi:[1,0] neg_lo:[0,1] neg_hi:[0,1]
	v_pk_add_f32 v[60:61], v[138:139], v[90:91] op_sel_hi:[1,0] neg_lo:[0,1] neg_hi:[0,1]
	v_pk_add_f32 v[62:63], v[134:135], v[90:91] op_sel_hi:[1,0] neg_lo:[0,1] neg_hi:[0,1]
	v_pk_add_f32 v[64:65], v[116:117], v[90:91] op_sel_hi:[1,0] neg_lo:[0,1] neg_hi:[0,1]
	v_pk_mul_f32 v[102:103], v[142:143], v[142:143]
	v_add_f32_e32 v90, v100, v101
	v_add_f32_e32 v90, v102, v90
	v_pk_mul_f32 v[116:117], v[144:145], v[144:145]
	v_add_f32_e32 v90, v103, v90
	v_add_f32_e32 v90, v116, v90
	v_pk_mul_f32 v[118:119], v[146:147], v[146:147]
	v_add_f32_e32 v90, v117, v90
	v_add_f32_e32 v90, v118, v90
	v_pk_mul_f32 v[120:121], v[106:107], v[106:107]
	v_add_f32_e32 v90, v119, v90
	v_add_f32_e32 v90, v120, v90
	v_pk_mul_f32 v[122:123], v[148:149], v[148:149]
	v_add_f32_e32 v90, v121, v90
	v_add_f32_e32 v90, v122, v90
	v_pk_mul_f32 v[124:125], v[104:105], v[104:105]
	v_add_f32_e32 v90, v123, v90
	v_add_f32_e32 v90, v124, v90
	v_pk_mul_f32 v[126:127], v[150:151], v[150:151]
	v_add_f32_e32 v90, v125, v90
	v_add_f32_e32 v90, v126, v90
	v_pk_mul_f32 v[128:129], v[110:111], v[110:111]
	v_add_f32_e32 v90, v127, v90
	v_add_f32_e32 v90, v128, v90
	v_pk_mul_f32 v[130:131], v[152:153], v[152:153]
	v_add_f32_e32 v90, v129, v90
	v_add_f32_e32 v90, v130, v90
	v_pk_mul_f32 v[132:133], v[108:109], v[108:109]
	v_add_f32_e32 v90, v131, v90
	v_add_f32_e32 v90, v132, v90
	v_pk_mul_f32 v[134:135], v[154:155], v[154:155]
	v_add_f32_e32 v90, v133, v90
	v_add_f32_e32 v90, v134, v90
	v_pk_mul_f32 v[136:137], v[114:115], v[114:115]
	v_add_f32_e32 v90, v135, v90
	v_add_f32_e32 v90, v136, v90
	v_pk_mul_f32 v[138:139], v[156:157], v[156:157]
	v_add_f32_e32 v90, v137, v90
	v_add_f32_e32 v90, v138, v90
	v_pk_mul_f32 v[160:161], v[112:113], v[112:113]
	v_add_f32_e32 v90, v139, v90
	v_add_f32_e32 v90, v160, v90
	v_pk_mul_f32 v[162:163], v[158:159], v[158:159]
	v_add_f32_e32 v90, v161, v90
	v_add_f32_e32 v90, v162, v90
	v_pk_mul_f32 v[164:165], v[82:83], v[82:83]
	v_add_f32_e32 v90, v163, v90
	v_add_f32_e32 v90, v164, v90
	v_pk_mul_f32 v[166:167], v[84:85], v[84:85]
	v_add_f32_e32 v90, v165, v90
	v_add_f32_e32 v90, v166, v90
	v_pk_mul_f32 v[168:169], v[86:87], v[86:87]
	v_add_f32_e32 v90, v167, v90
	v_add_f32_e32 v90, v168, v90
	v_pk_mul_f32 v[170:171], v[88:89], v[88:89]
	v_add_f32_e32 v90, v169, v90
	v_add_f32_e32 v90, v170, v90
	v_pk_mul_f32 v[172:173], v[74:75], v[74:75]
	v_add_f32_e32 v90, v171, v90
	v_add_f32_e32 v90, v172, v90
	v_pk_mul_f32 v[174:175], v[76:77], v[76:77]
	v_add_f32_e32 v90, v173, v90
	v_add_f32_e32 v90, v174, v90
	v_pk_mul_f32 v[176:177], v[78:79], v[78:79]
	v_add_f32_e32 v90, v175, v90
	v_add_f32_e32 v90, v176, v90
	v_pk_mul_f32 v[178:179], v[80:81], v[80:81]
	v_add_f32_e32 v90, v177, v90
	v_add_f32_e32 v90, v178, v90
	v_pk_mul_f32 v[180:181], v[66:67], v[66:67]
	v_add_f32_e32 v90, v179, v90
	v_add_f32_e32 v90, v180, v90
	v_pk_mul_f32 v[182:183], v[68:69], v[68:69]
	v_add_f32_e32 v90, v181, v90
	v_add_f32_e32 v90, v182, v90
	v_pk_mul_f32 v[184:185], v[70:71], v[70:71]
	v_add_f32_e32 v90, v183, v90
	v_add_f32_e32 v90, v184, v90
	v_pk_mul_f32 v[186:187], v[72:73], v[72:73]
	v_add_f32_e32 v90, v185, v90
	v_add_f32_e32 v90, v186, v90
	v_pk_mul_f32 v[188:189], v[58:59], v[58:59]
	v_add_f32_e32 v90, v187, v90
	v_add_f32_e32 v90, v188, v90
	v_pk_mul_f32 v[190:191], v[60:61], v[60:61]
	v_add_f32_e32 v90, v189, v90
	v_add_f32_e32 v90, v190, v90
	v_pk_mul_f32 v[194:195], v[62:63], v[62:63]
	v_add_f32_e32 v90, v191, v90
	v_add_f32_e32 v90, v194, v90
	v_pk_mul_f32 v[196:197], v[64:65], v[64:65]
	v_add_f32_e32 v90, v195, v90
	v_add_f32_e32 v90, v197, v90
	v_add_f32_e32 v90, v196, v90
	ds_bpermute_b32 v99, v91, v90
	s_waitcnt lgkmcnt(0)
; __device__ __forceinline__ unsigned pk2(float lo, float hi) { const bf16x2_t v = __builtin_convertvector((f32x2_t){lo, hi}, bf16x2_t); return __builtin_bit_cast(unsigned, v); }
; template <bool FINAL>
; __device__ __forceinline__ void ln_phase(const bf16_t* pre, const float* gam, const float* bet, float* outf, bf16_t* outb, int wave) {
;     ...
;         for (int o = 1; o < 64; o <<= 1) q += __shfl_xor(q, o);
;         const float rstd = 1.0f / sqrtf(q * (1.0f / DM) + LN_EPS);
; #pragma unroll
;         for (int j = 0; j < 8; ++j) {
;             const int c0 = 8 * (lane + 64 * j);
;             const f32x4 g0 = *(const f32x4*)(gam + c0), g1 = *(const f32x4*)(gam + c0 + 4), b0 = *(const f32x4*)(bet + c0), b1 = *(const f32x4*)(bet + c0 + 4);
;             const f32x4 y0 = (f32x4){v[j][0], v[j][1], v[j][2], v[j][3]} * rstd * g0 + b0, y1 = (f32x4){v[j][4], v[j][5], v[j][6], v[j][7]} * rstd * g1 + b1;
;             if (FINAL) { float* o = outf + (size_t)row * DM + c0; *(f32x4*)o = y0; *(f32x4*)(o + 4) = y1; }
;             else { u32x4 w; w.x = pk2(y0.x, y0.y); w.y = pk2(y0.z, y0.w); w.z = pk2(y1.x, y1.y); w.w = pk2(y1.z, y1.w); *(u32x4*)(outb + (size_t)row * DM + c0) = w; }
	v_add_f32_e32 v90, v90, v99
	ds_bpermute_b32 v99, v92, v90
	s_waitcnt lgkmcnt(0)
	v_add_f32_e32 v90, v90, v99
	ds_bpermute_b32 v99, v93, v90
	s_waitcnt lgkmcnt(0)
	v_add_f32_e32 v90, v90, v99
	ds_bpermute_b32 v99, v94, v90
	s_waitcnt lgkmcnt(0)
	v_add_f32_e32 v90, v90, v99
	ds_bpermute_b32 v99, v95, v90
	s_waitcnt lgkmcnt(0)
	v_add_f32_e32 v90, v90, v99
	ds_bpermute_b32 v99, v96, v90
	s_waitcnt lgkmcnt(0)
	v_add_f32_e32 v90, v90, v99
	v_fmamk_f32 v90, v90, 0x39800000, v97
	v_mul_f32_e32 v99, 0x4f800000, v90
	v_cmp_gt_f32_e32 vcc, s4, v90
	s_nop 1
	v_cndmask_b32_e32 v90, v90, v99, vcc
	v_sqrt_f32_e32 v99, v90
	s_nop 0
	v_add_u32_e32 v100, -1, v99
	v_add_u32_e32 v101, 1, v99
	v_fma_f32 v102, -v100, v99, v90
	v_fma_f32 v103, -v101, v99, v90
	v_cmp_ge_f32_e64 s[6:7], 0, v102
	s_nop 1
	v_cndmask_b32_e64 v99, v99, v100, s[6:7]
	v_cmp_lt_f32_e64 s[6:7], 0, v103
	s_nop 1
	v_cndmask_b32_e64 v99, v99, v101, s[6:7]
	v_mul_f32_e32 v100, 0x37800000, v99
	v_cndmask_b32_e32 v99, v99, v100, vcc
	v_cmp_class_f32_e32 vcc, v90, v98
	s_nop 1
	v_cndmask_b32_e32 v90, v99, v90, vcc
	v_div_scale_f32 v99, s[6:7], v90, v90, 1.0
	v_rcp_f32_e32 v101, v99
	v_div_scale_f32 v100, vcc, 1.0, v90, 1.0
	v_fma_f32 v102, -v99, v101, 1.0
	v_fmac_f32_e32 v101, v102, v101
	v_mul_f32_e32 v102, v100, v101
	v_fma_f32 v103, -v99, v102, v100
	v_fmac_f32_e32 v102, v103, v101
	v_fma_f32 v99, -v99, v102, v100
	v_div_fmas_f32 v99, v99, v101, v102
	v_div_fixup_f32 v90, v99, v90, 1.0
	v_pk_mul_f32 v[100:101], v[140:141], v[90:91] op_sel_hi:[1,0]
	v_pk_mul_f32 v[102:103], v[142:143], v[90:91] op_sel_hi:[1,0]
	v_pk_mul_f32 v[116:117], v[144:145], v[90:91] op_sel_hi:[1,0]
	v_pk_mul_f32 v[118:119], v[146:147], v[90:91] op_sel_hi:[1,0]
	v_pk_fma_f32 v[6:7], v[6:7], v[102:103], v[14:15]
	v_pk_fma_f32 v[4:5], v[4:5], v[100:101], v[12:13]
	v_pk_fma_f32 v[10:11], v[2:3], v[118:119], v[10:11]
	v_pk_fma_f32 v[2:3], v[0:1], v[116:117], v[8:9]
	v_cvt_pk_bf16_f32 v0, v4, v5
	v_cvt_pk_bf16_f32 v1, v6, v7
	v_cvt_pk_bf16_f32 v2, v2, v3
	v_cvt_pk_bf16_f32 v3, v10, v11
	global_store_dwordx4 v[56:57], v[0:3], off
	global_load_dwordx4 v[0:3], v[22:23], off
	s_nop 0
	global_load_dwordx4 v[4:7], v[20:21], off
	global_load_dwordx4 v[8:11], v[20:21], off offset:16
	global_load_dwordx4 v[12:15], v[22:23], off offset:16
	v_pk_mul_f32 v[100:101], v[106:107], v[90:91] op_sel_hi:[1,0]
	v_pk_mul_f32 v[102:103], v[148:149], v[90:91] op_sel_hi:[1,0]
	v_pk_mul_f32 v[104:105], v[104:105], v[90:91] op_sel_hi:[1,0]
	v_pk_mul_f32 v[106:107], v[150:151], v[90:91] op_sel_hi:[1,0]
	v_pk_mul_f32 v[82:83], v[82:83], v[90:91] op_sel_hi:[1,0]
	v_pk_mul_f32 v[84:85], v[84:85], v[90:91] op_sel_hi:[1,0]
	v_pk_mul_f32 v[86:87], v[86:87], v[90:91] op_sel_hi:[1,0]
	v_pk_mul_f32 v[88:89], v[88:89], v[90:91] op_sel_hi:[1,0]
	v_pk_mul_f32 v[74:75], v[74:75], v[90:91] op_sel_hi:[1,0]
	v_pk_mul_f32 v[76:77], v[76:77], v[90:91] op_sel_hi:[1,0]
	v_pk_mul_f32 v[78:79], v[78:79], v[90:91] op_sel_hi:[1,0]
	v_pk_mul_f32 v[80:81], v[80:81], v[90:91] op_sel_hi:[1,0]
	v_pk_mul_f32 v[66:67], v[66:67], v[90:91] op_sel_hi:[1,0]
	v_pk_mul_f32 v[68:69], v[68:69], v[90:91] op_sel_hi:[1,0]
	v_pk_mul_f32 v[70:71], v[70:71], v[90:91] op_sel_hi:[1,0]
	v_pk_mul_f32 v[72:73], v[72:73], v[90:91] op_sel_hi:[1,0]
	v_pk_mul_f32 v[58:59], v[58:59], v[90:91] op_sel_hi:[1,0]
	v_pk_mul_f32 v[60:61], v[60:61], v[90:91] op_sel_hi:[1,0]
	v_pk_mul_f32 v[62:63], v[62:63], v[90:91] op_sel_hi:[1,0]
	v_pk_mul_f32 v[64:65], v[64:65], v[90:91] op_sel:[1,0] op_sel_hi:[0,0]
	v_pk_fma_f32 v[202:203], v[206:207], v[102:103], v[202:203]
	v_pk_fma_f32 v[200:201], v[204:205], v[100:101], v[200:201]
	v_pk_fma_f32 v[204:205], v[210:211], v[106:107], v[214:215]
	v_pk_fma_f32 v[206:207], v[208:209], v[104:105], v[212:213]
	v_cvt_pk_bf16_f32 v200, v200, v201
	v_cvt_pk_bf16_f32 v201, v202, v203
	v_cvt_pk_bf16_f32 v202, v206, v207
	v_cvt_pk_bf16_f32 v203, v204, v205
	global_store_dwordx4 v[56:57], v[200:203], off offset:1024
	global_load_dwordx4 v[200:203], v[26:27], off
	s_nop 0
	global_load_dwordx4 v[204:207], v[24:25], off
	global_load_dwordx4 v[208:211], v[24:25], off offset:16
	global_load_dwordx4 v[212:215], v[26:27], off offset:16
	v_pk_mul_f32 v[100:101], v[110:111], v[90:91] op_sel_hi:[1,0]
	v_pk_mul_f32 v[102:103], v[152:153], v[90:91] op_sel_hi:[1,0]
	v_pk_mul_f32 v[104:105], v[108:109], v[90:91] op_sel_hi:[1,0]
	v_pk_mul_f32 v[106:107], v[154:155], v[90:91] op_sel_hi:[1,0]
	s_waitcnt vmcnt(5)
; __device__ __forceinline__ unsigned pk2(float lo, float hi) { const bf16x2_t v = __builtin_convertvector((f32x2_t){lo, hi}, bf16x2_t); return __builtin_bit_cast(unsigned, v); }
; template <bool FINAL>
; __device__ __forceinline__ void ln_phase(const bf16_t* pre, const float* gam, const float* bet, float* outf, bf16_t* outb, int wave) {
;     ...
; #pragma unroll
;         for (int j = 0; j < 8; ++j) {
;             const int c0 = 8 * (lane + 64 * j);
;             const f32x4 g0 = *(const f32x4*)(gam + c0), g1 = *(const f32x4*)(gam + c0 + 4), b0 = *(const f32x4*)(bet + c0), b1 = *(const f32x4*)(bet + c0 + 4);
;             const f32x4 y0 = (f32x4){v[j][0], v[j][1], v[j][2], v[j][3]} * rstd * g0 + b0, y1 = (f32x4){v[j][4], v[j][5], v[j][6], v[j][7]} * rstd * g1 + b1;
;             if (FINAL) { float* o = outf + (size_t)row * DM + c0; *(f32x4*)o = y0; *(f32x4*)(o + 4) = y1; }
;             else { u32x4 w; w.x = pk2(y0.x, y0.y); w.y = pk2(y0.z, y0.w); w.z = pk2(y1.x, y1.y); w.w = pk2(y1.z, y1.w); *(u32x4*)(outb + (size_t)row * DM + c0) = w; }
;         }
;     }
	v_pk_fma_f32 v[2:3], v[6:7], v[102:103], v[2:3]
	v_pk_fma_f32 v[0:1], v[4:5], v[100:101], v[0:1]
	v_pk_fma_f32 v[4:5], v[10:11], v[106:107], v[14:15]
	v_pk_fma_f32 v[6:7], v[8:9], v[104:105], v[12:13]
	v_cvt_pk_bf16_f32 v0, v0, v1
	v_cvt_pk_bf16_f32 v1, v2, v3
	v_cvt_pk_bf16_f32 v2, v6, v7
	v_cvt_pk_bf16_f32 v3, v4, v5
	global_store_dwordx4 v[56:57], v[0:3], off offset:2048
	global_load_dwordx4 v[0:3], v[30:31], off
	s_nop 0
	global_load_dwordx4 v[4:7], v[28:29], off
	global_load_dwordx4 v[8:11], v[28:29], off offset:16
	global_load_dwordx4 v[12:15], v[30:31], off offset:16
	v_pk_mul_f32 v[100:101], v[114:115], v[90:91] op_sel_hi:[1,0]
	v_pk_mul_f32 v[102:103], v[156:157], v[90:91] op_sel_hi:[1,0]
	v_pk_mul_f32 v[104:105], v[112:113], v[90:91] op_sel_hi:[1,0]
	v_pk_mul_f32 v[106:107], v[158:159], v[90:91] op_sel_hi:[1,0]
	s_waitcnt vmcnt(5)
	v_pk_fma_f32 v[202:203], v[206:207], v[102:103], v[202:203]
	v_pk_fma_f32 v[200:201], v[204:205], v[100:101], v[200:201]
	v_pk_fma_f32 v[204:205], v[210:211], v[106:107], v[214:215]
	v_pk_fma_f32 v[206:207], v[208:209], v[104:105], v[212:213]
	v_cvt_pk_bf16_f32 v200, v200, v201
	v_cvt_pk_bf16_f32 v201, v202, v203
	v_cvt_pk_bf16_f32 v202, v206, v207
	v_cvt_pk_bf16_f32 v203, v204, v205
	global_store_dwordx4 v[56:57], v[200:203], off offset:3072
	global_load_dwordx4 v[200:203], v[34:35], off
	s_nop 0
	global_load_dwordx4 v[204:207], v[32:33], off
	global_load_dwordx4 v[208:211], v[32:33], off offset:16
	global_load_dwordx4 v[212:215], v[34:35], off offset:16
	v_lshl_add_u64 v[56:57], s[8:9], 0, v[50:51]
	s_waitcnt vmcnt(5)
	v_pk_fma_f32 v[2:3], v[6:7], v[84:85], v[2:3]
	v_pk_fma_f32 v[0:1], v[4:5], v[82:83], v[0:1]
	v_pk_fma_f32 v[4:5], v[10:11], v[88:89], v[14:15]
	v_pk_fma_f32 v[6:7], v[8:9], v[86:87], v[12:13]
	v_cvt_pk_bf16_f32 v0, v0, v1
	v_cvt_pk_bf16_f32 v1, v2, v3
	v_cvt_pk_bf16_f32 v2, v6, v7
	v_cvt_pk_bf16_f32 v3, v4, v5
	global_store_dwordx4 v[56:57], v[0:3], off
	global_load_dwordx4 v[0:3], v[38:39], off
	s_nop 0
	global_load_dwordx4 v[4:7], v[36:37], off
	global_load_dwordx4 v[8:11], v[36:37], off offset:16
	global_load_dwordx4 v[12:15], v[38:39], off offset:16
	v_lshl_add_u64 v[56:57], s[8:9], 0, v[48:49]
	s_waitcnt vmcnt(5)
	v_pk_fma_f32 v[202:203], v[206:207], v[76:77], v[202:203]
	v_pk_fma_f32 v[200:201], v[204:205], v[74:75], v[200:201]
	v_pk_fma_f32 v[204:205], v[210:211], v[80:81], v[214:215]
	v_pk_fma_f32 v[206:207], v[208:209], v[78:79], v[212:213]
	v_cvt_pk_bf16_f32 v200, v200, v201
	v_cvt_pk_bf16_f32 v201, v202, v203
	v_cvt_pk_bf16_f32 v202, v206, v207
	v_cvt_pk_bf16_f32 v203, v204, v205
	global_store_dwordx4 v[56:57], v[200:203], off
	global_load_dwordx4 v[200:203], v[42:43], off
	s_nop 0
	global_load_dwordx4 v[204:207], v[40:41], off
	global_load_dwordx4 v[208:211], v[40:41], off offset:16
	global_load_dwordx4 v[212:215], v[42:43], off offset:16
	v_lshl_add_u64 v[56:57], s[8:9], 0, v[46:47]
	s_waitcnt vmcnt(5)
	v_pk_fma_f32 v[2:3], v[6:7], v[68:69], v[2:3]
	v_pk_fma_f32 v[0:1], v[4:5], v[66:67], v[0:1]
	v_pk_fma_f32 v[4:5], v[10:11], v[72:73], v[14:15]
	v_pk_fma_f32 v[6:7], v[8:9], v[70:71], v[12:13]
	v_cvt_pk_bf16_f32 v0, v0, v1
	v_cvt_pk_bf16_f32 v1, v2, v3
	v_cvt_pk_bf16_f32 v2, v6, v7
	v_cvt_pk_bf16_f32 v3, v4, v5
	global_store_dwordx4 v[56:57], v[0:3], off
	v_lshl_add_u64 v[56:57], s[8:9], 0, v[44:45]
	s_add_u32 s8, s8, s10
	s_addc_u32 s9, s9, s11
	s_cmpk_lt_i32 s12, 0x2100
	s_waitcnt vmcnt(1)
	v_pk_fma_f32 v[202:203], v[206:207], v[60:61], v[202:203]
	v_pk_fma_f32 v[200:201], v[204:205], v[58:59], v[200:201]
	v_pk_fma_f32 v[204:205], v[210:211], v[64:65], v[214:215]
	v_pk_fma_f32 v[206:207], v[208:209], v[62:63], v[212:213]
	v_cvt_pk_bf16_f32 v200, v200, v201
	v_cvt_pk_bf16_f32 v201, v202, v203
	v_cvt_pk_bf16_f32 v202, v206, v207
	v_cvt_pk_bf16_f32 v203, v204, v205
	global_store_dwordx4 v[56:57], v[200:203], off
	s_cbranch_scc1 .LBB0_1019

; __device__ __forceinline__ void bf8_unpack(const u32x4 x, float (&f)[8]) { f[0] = bf_lo(x.x); f[1] = bf_hi(x.x); f[2] = bf_lo(x.y); f[3] = bf_hi(x.y); f[4] = bf_lo(x.z); f[5] = bf_hi(x.z); f[6] = bf_lo(x.w); f[7] = bf_hi(x.w); }
; template <bool FINAL>
; __device__ __forceinline__ void ln_phase(const bf16_t* pre, const float* gam, const float* bet, float* outf, bf16_t* outb, int wave) {
;     ...
;     for (int row = gw; row < NTOK; row += NGW) {
;         const u32x4* src = (const u32x4*)(pre + (size_t)row * DM) + lane;
;         float v[8][8]; float s = 0.f;
; #pragma unroll
;         for (int j = 0; j < 8; ++j) { const u32x4 x = src[64 * j]; bf8_unpack(x, v[j]);
; #pragma unroll
;             for (int e = 0; e < 8; ++e) s += v[j][e]; }
; #pragma unroll
;         for (int o = 1; o < 64; o <<= 1) s += __shfl_xor(s, o);
;         const float mean = s * (1.0f / DM); float q = 0.f;
;     ...
;         for (int j = 0; j < 8; ++j) {
;             const int c0 = 8 * (lane + 64 * j);
;             const f32x4 g0 = *(const f32x4*)(gam + c0), g1 = *(const f32x4*)(gam + c0 + 4), b0 = *(const f32x4*)(bet + c0), b1 = *(const f32x4*)(bet + c0 + 4);
.LBB0_1363:
	v_add_co_u32_e32 v60, vcc, 0xffffe400, v58
	global_load_dwordx4 v[4:7], v[18:19], off
	global_load_dwordx4 v[0:3], v[18:19], off offset:16
	global_load_dwordx4 v[12:15], v[20:21], off
	global_load_dwordx4 v[8:11], v[20:21], off offset:16
	v_addc_co_u32_e32 v61, vcc, -1, v59, vcc
	v_add_co_u32_e32 v64, vcc, 0xffffe800, v58
	global_load_dwordx4 v[60:63], v[60:61], off
	s_nop 0
	v_addc_co_u32_e32 v65, vcc, -1, v59, vcc
	v_add_co_u32_e32 v70, vcc, 0xffffec00, v58
	global_load_dwordx4 v[64:67], v[64:65], off
	s_nop 0
	v_addc_co_u32_e32 v71, vcc, -1, v59, vcc
	v_add_co_u32_e32 v74, vcc, 0xfffff000, v58
	global_load_dwordx4 v[70:73], v[70:71], off
	s_nop 0
	v_addc_co_u32_e32 v75, vcc, -1, v59, vcc
	v_add_co_u32_e32 v78, vcc, 0xfffff400, v58
	global_load_dwordx4 v[74:77], v[74:75], off
	s_nop 0
	v_addc_co_u32_e32 v79, vcc, -1, v59, vcc
	v_add_co_u32_e32 v82, vcc, 0xfffff800, v58
	global_load_dwordx4 v[78:81], v[78:79], off
	s_nop 0
	v_addc_co_u32_e32 v83, vcc, -1, v59, vcc
	v_add_co_u32_e32 v96, vcc, 0xfffffc00, v58
	global_load_dwordx4 v[82:85], v[82:83], off
	s_nop 0
	v_addc_co_u32_e32 v97, vcc, -1, v59, vcc
	global_load_dwordx4 v[86:89], v[58:59], off
	global_load_dwordx4 v[90:93], v[96:97], off
	v_lshl_add_u64 v[68:69], s[4:5], 0, v[16:17]
	s_add_i32 s38, s38, s40
	v_lshl_add_u64 v[58:59], v[58:59], 0, s[2:3]
	global_load_dwordx4 v[200:203], v[20:21], off offset:2048
	global_load_dwordx4 v[204:207], v[18:19], off offset:2048
	global_load_dwordx4 v[208:211], v[18:19], off offset:2064
	global_load_dwordx4 v[212:215], v[20:21], off offset:2064
	s_waitcnt vmcnt(0) lgkmcnt(0)
	v_lshlrev_b32_e32 v98, 16, v60
	v_and_b32_e32 v99, 0xffff0000, v60
	v_add_f32_e32 v94, 0, v98
	v_lshlrev_b32_e32 v60, 16, v61
	v_add_f32_e32 v94, v94, v99
	v_and_b32_e32 v61, 0xffff0000, v61
	v_add_f32_e32 v94, v94, v60
	v_lshlrev_b32_e32 v96, 16, v62
	v_add_f32_e32 v94, v94, v61
	v_and_b32_e32 v97, 0xffff0000, v62
	v_add_f32_e32 v94, v94, v96
	v_lshlrev_b32_e32 v62, 16, v63
	v_add_f32_e32 v94, v94, v97
	v_and_b32_e32 v63, 0xffff0000, v63
	v_lshlrev_b32_e32 v102, 16, v64
	v_and_b32_e32 v103, 0xffff0000, v64
	v_lshlrev_b32_e32 v64, 16, v65
	v_and_b32_e32 v65, 0xffff0000, v65
	v_lshlrev_b32_e32 v100, 16, v66
	v_and_b32_e32 v101, 0xffff0000, v66
	v_lshlrev_b32_e32 v66, 16, v67
	v_and_b32_e32 v67, 0xffff0000, v67
	v_lshlrev_b32_e32 v114, 16, v70
	v_and_b32_e32 v115, 0xffff0000, v70
	v_lshlrev_b32_e32 v70, 16, v71
	v_and_b32_e32 v71, 0xffff0000, v71
	v_lshlrev_b32_e32 v112, 16, v72
	v_lshlrev_b32_e32 v140, 16, v86
	v_and_b32_e32 v141, 0xffff0000, v86
	v_add_f32_e32 v86, v94, v62
	v_add_f32_e32 v86, v86, v63
	v_add_f32_e32 v86, v86, v102
	v_add_f32_e32 v86, v86, v103
	v_add_f32_e32 v86, v86, v64
	v_add_f32_e32 v86, v86, v65
	v_add_f32_e32 v86, v86, v100
	v_add_f32_e32 v86, v86, v101
	v_add_f32_e32 v86, v86, v66
	v_add_f32_e32 v86, v86, v67
	v_add_f32_e32 v86, v86, v114
	v_add_f32_e32 v86, v86, v115
	v_add_f32_e32 v86, v86, v70
	v_add_f32_e32 v86, v86, v71
	v_and_b32_e32 v113, 0xffff0000, v72
	v_add_f32_e32 v86, v86, v112
	v_lshlrev_b32_e32 v72, 16, v73
	v_add_f32_e32 v86, v86, v113
	v_and_b32_e32 v73, 0xffff0000, v73
	v_add_f32_e32 v86, v86, v72
	v_lshlrev_b32_e32 v118, 16, v74
	v_add_f32_e32 v86, v86, v73
	v_and_b32_e32 v119, 0xffff0000, v74
	v_add_f32_e32 v86, v86, v118
	v_lshlrev_b32_e32 v74, 16, v75
	v_add_f32_e32 v86, v86, v119
	v_and_b32_e32 v75, 0xffff0000, v75
	v_add_f32_e32 v86, v86, v74
	v_lshlrev_b32_e32 v116, 16, v76
	v_add_f32_e32 v86, v86, v75
	v_and_b32_e32 v117, 0xffff0000, v76
	v_add_f32_e32 v86, v86, v116
	v_lshlrev_b32_e32 v76, 16, v77
	v_add_f32_e32 v86, v86, v117
	v_and_b32_e32 v77, 0xffff0000, v77
	v_add_f32_e32 v86, v86, v76
	v_lshlrev_b32_e32 v122, 16, v78
	v_add_f32_e32 v86, v86, v77
	v_and_b32_e32 v123, 0xffff0000, v78
	v_add_f32_e32 v86, v86, v122
	v_lshlrev_b32_e32 v78, 16, v79
	v_add_f32_e32 v86, v86, v123
	v_and_b32_e32 v79, 0xffff0000, v79
	v_add_f32_e32 v86, v86, v78
	v_lshlrev_b32_e32 v120, 16, v80
	v_add_f32_e32 v86, v86, v79
	v_and_b32_e32 v121, 0xffff0000, v80
	v_add_f32_e32 v86, v86, v120
	v_lshlrev_b32_e32 v80, 16, v81
	v_add_f32_e32 v86, v86, v121
	v_and_b32_e32 v81, 0xffff0000, v81
	v_add_f32_e32 v86, v86, v80
	v_lshlrev_b32_e32 v126, 16, v82
	v_add_f32_e32 v86, v86, v81
	v_and_b32_e32 v127, 0xffff0000, v82
	v_add_f32_e32 v86, v86, v126
	v_lshlrev_b32_e32 v82, 16, v83
	v_add_f32_e32 v86, v86, v127
	v_and_b32_e32 v83, 0xffff0000, v83
	v_add_f32_e32 v86, v86, v82
	v_lshlrev_b32_e32 v124, 16, v84
	v_add_f32_e32 v86, v86, v83
	v_and_b32_e32 v125, 0xffff0000, v84
	v_add_f32_e32 v86, v86, v124
	v_lshlrev_b32_e32 v84, 16, v85
	v_add_f32_e32 v86, v86, v125
	v_and_b32_e32 v85, 0xffff0000, v85
	v_add_f32_e32 v86, v86, v84
	v_lshlrev_b32_e32 v134, 16, v90
	v_add_f32_e32 v86, v86, v85
	v_and_b32_e32 v135, 0xffff0000, v90
	v_add_f32_e32 v86, v86, v134
	v_lshlrev_b32_e32 v136, 16, v91
	v_add_f32_e32 v86, v86, v135
	v_and_b32_e32 v137, 0xffff0000, v91
	v_add_f32_e32 v86, v86, v136
	v_lshlrev_b32_e32 v130, 16, v92
	v_add_f32_e32 v86, v86, v137
	v_and_b32_e32 v131, 0xffff0000, v92
	v_add_f32_e32 v86, v86, v130
	v_lshlrev_b32_e32 v132, 16, v93
	v_add_f32_e32 v86, v86, v131
	v_and_b32_e32 v133, 0xffff0000, v93
	v_add_f32_e32 v86, v86, v132
	v_add_f32_e32 v86, v86, v133
	v_add_f32_e32 v86, v86, v140
	v_lshlrev_b32_e32 v142, 16, v87
	v_add_f32_e32 v86, v86, v141
	v_and_b32_e32 v143, 0xffff0000, v87
	v_add_f32_e32 v86, v86, v142
	v_lshlrev_b32_e32 v138, 16, v88
	v_add_f32_e32 v86, v86, v143
	v_and_b32_e32 v139, 0xffff0000, v88
	v_add_f32_e32 v86, v86, v138
	v_lshlrev_b32_e32 v129, 16, v89
	v_add_f32_e32 v86, v86, v139
	v_and_b32_e32 v128, 0xffff0000, v89
	v_add_f32_e32 v86, v86, v129
	v_add_f32_e32 v86, v86, v128
	ds_bpermute_b32 v87, v95, v86
	s_waitcnt lgkmcnt(0)
; template <bool FINAL>
; __device__ __forceinline__ void ln_phase(const bf16_t* pre, const float* gam, const float* bet, float* outf, bf16_t* outb, int wave) {
;     ...
;         for (int o = 1; o < 64; o <<= 1) s += __shfl_xor(s, o);
;         const float mean = s * (1.0f / DM); float q = 0.f;
; #pragma unroll
;         for (int j = 0; j < 8; ++j)
; #pragma unroll
;             for (int e = 0; e < 8; ++e) { v[j][e] -= mean; q += v[j][e] * v[j][e]; }
; #pragma unroll
;         for (int o = 1; o < 64; o <<= 1) q += __shfl_xor(q, o);
	v_add_f32_e32 v86, v86, v87
	ds_bpermute_b32 v87, v104, v86
	s_waitcnt lgkmcnt(0)
	v_add_f32_e32 v86, v86, v87
	ds_bpermute_b32 v87, v105, v86
	s_waitcnt lgkmcnt(0)
	v_add_f32_e32 v86, v86, v87
	ds_bpermute_b32 v87, v106, v86
	s_waitcnt lgkmcnt(0)
	v_add_f32_e32 v86, v86, v87
	ds_bpermute_b32 v87, v107, v86
	s_waitcnt lgkmcnt(0)
	v_add_f32_e32 v86, v86, v87
	ds_bpermute_b32 v87, v108, v86
	s_waitcnt lgkmcnt(0)
	v_add_f32_e32 v86, v86, v87
	v_mul_f32_e32 v94, 0x39800000, v86
	v_pk_add_f32 v[144:145], v[98:99], v[94:95] op_sel_hi:[1,0] neg_lo:[0,1] neg_hi:[0,1]
	v_pk_add_f32 v[146:147], v[60:61], v[94:95] op_sel_hi:[1,0] neg_lo:[0,1] neg_hi:[0,1]
	v_pk_add_f32 v[98:99], v[116:117], v[94:95] op_sel_hi:[1,0] neg_lo:[0,1] neg_hi:[0,1]
	v_pk_mul_f32 v[116:117], v[144:145], v[144:145]
	v_pk_add_f32 v[148:149], v[96:97], v[94:95] op_sel_hi:[1,0] neg_lo:[0,1] neg_hi:[0,1]
	v_pk_add_f32 v[150:151], v[62:63], v[94:95] op_sel_hi:[1,0] neg_lo:[0,1] neg_hi:[0,1]
	v_pk_add_f32 v[152:153], v[102:103], v[94:95] op_sel_hi:[1,0] neg_lo:[0,1] neg_hi:[0,1]
	v_pk_add_f32 v[154:155], v[64:65], v[94:95] op_sel_hi:[1,0] neg_lo:[0,1] neg_hi:[0,1]
	v_pk_add_f32 v[156:157], v[100:101], v[94:95] op_sel_hi:[1,0] neg_lo:[0,1] neg_hi:[0,1]
	v_pk_add_f32 v[158:159], v[66:67], v[94:95] op_sel_hi:[1,0] neg_lo:[0,1] neg_hi:[0,1]
	v_pk_add_f32 v[114:115], v[114:115], v[94:95] op_sel_hi:[1,0] neg_lo:[0,1] neg_hi:[0,1]
	v_pk_add_f32 v[160:161], v[70:71], v[94:95] op_sel_hi:[1,0] neg_lo:[0,1] neg_hi:[0,1]
	v_pk_add_f32 v[112:113], v[112:113], v[94:95] op_sel_hi:[1,0] neg_lo:[0,1] neg_hi:[0,1]
	v_pk_add_f32 v[162:163], v[72:73], v[94:95] op_sel_hi:[1,0] neg_lo:[0,1] neg_hi:[0,1]
	v_pk_add_f32 v[96:97], v[118:119], v[94:95] op_sel_hi:[1,0] neg_lo:[0,1] neg_hi:[0,1]
	v_pk_add_f32 v[100:101], v[74:75], v[94:95] op_sel_hi:[1,0] neg_lo:[0,1] neg_hi:[0,1]
	v_pk_add_f32 v[102:103], v[76:77], v[94:95] op_sel_hi:[1,0] neg_lo:[0,1] neg_hi:[0,1]
	v_pk_add_f32 v[86:87], v[122:123], v[94:95] op_sel_hi:[1,0] neg_lo:[0,1] neg_hi:[0,1]
	v_pk_add_f32 v[90:91], v[78:79], v[94:95] op_sel_hi:[1,0] neg_lo:[0,1] neg_hi:[0,1]
	v_pk_add_f32 v[88:89], v[120:121], v[94:95] op_sel_hi:[1,0] neg_lo:[0,1] neg_hi:[0,1]
	v_pk_add_f32 v[92:93], v[80:81], v[94:95] op_sel_hi:[1,0] neg_lo:[0,1] neg_hi:[0,1]
	v_pk_add_f32 v[78:79], v[126:127], v[94:95] op_sel_hi:[1,0] neg_lo:[0,1] neg_hi:[0,1]
	v_pk_add_f32 v[82:83], v[82:83], v[94:95] op_sel_hi:[1,0] neg_lo:[0,1] neg_hi:[0,1]
	v_pk_add_f32 v[80:81], v[124:125], v[94:95] op_sel_hi:[1,0] neg_lo:[0,1] neg_hi:[0,1]
	v_pk_add_f32 v[84:85], v[84:85], v[94:95] op_sel_hi:[1,0] neg_lo:[0,1] neg_hi:[0,1]
	v_pk_add_f32 v[70:71], v[134:135], v[94:95] op_sel_hi:[1,0] neg_lo:[0,1] neg_hi:[0,1]
	v_pk_add_f32 v[74:75], v[136:137], v[94:95] op_sel_hi:[1,0] neg_lo:[0,1] neg_hi:[0,1]
	v_pk_add_f32 v[72:73], v[130:131], v[94:95] op_sel_hi:[1,0] neg_lo:[0,1] neg_hi:[0,1]
	v_pk_add_f32 v[76:77], v[132:133], v[94:95] op_sel_hi:[1,0] neg_lo:[0,1] neg_hi:[0,1]
	v_pk_add_f32 v[60:61], v[140:141], v[94:95] op_sel_hi:[1,0] neg_lo:[0,1] neg_hi:[0,1]
	v_pk_add_f32 v[64:65], v[142:143], v[94:95] op_sel_hi:[1,0] neg_lo:[0,1] neg_hi:[0,1]
	v_pk_add_f32 v[62:63], v[138:139], v[94:95] op_sel_hi:[1,0] neg_lo:[0,1] neg_hi:[0,1]
	v_pk_add_f32 v[66:67], v[128:129], v[94:95] op_sel_hi:[1,0] neg_lo:[0,1] neg_hi:[0,1]
	v_pk_mul_f32 v[118:119], v[146:147], v[146:147]
	v_add_f32_e32 v94, v116, v117
	v_add_f32_e32 v94, v118, v94
	v_pk_mul_f32 v[120:121], v[148:149], v[148:149]
	v_add_f32_e32 v94, v119, v94
	v_add_f32_e32 v94, v120, v94
	v_pk_mul_f32 v[122:123], v[150:151], v[150:151]
	v_add_f32_e32 v94, v121, v94
	v_add_f32_e32 v94, v122, v94
	v_pk_mul_f32 v[124:125], v[152:153], v[152:153]
	v_add_f32_e32 v94, v123, v94
	v_add_f32_e32 v94, v124, v94
	v_pk_mul_f32 v[126:127], v[154:155], v[154:155]
	v_add_f32_e32 v94, v125, v94
	v_add_f32_e32 v94, v126, v94
	v_pk_mul_f32 v[128:129], v[156:157], v[156:157]
	v_add_f32_e32 v94, v127, v94
	v_add_f32_e32 v94, v128, v94
	v_pk_mul_f32 v[130:131], v[158:159], v[158:159]
	v_add_f32_e32 v94, v129, v94
	v_add_f32_e32 v94, v130, v94
	v_pk_mul_f32 v[132:133], v[114:115], v[114:115]
	v_add_f32_e32 v94, v131, v94
	v_add_f32_e32 v94, v132, v94
	v_pk_mul_f32 v[134:135], v[160:161], v[160:161]
	v_add_f32_e32 v94, v133, v94
	v_add_f32_e32 v94, v134, v94
	v_pk_mul_f32 v[136:137], v[112:113], v[112:113]
	v_add_f32_e32 v94, v135, v94
	v_add_f32_e32 v94, v136, v94
	v_pk_mul_f32 v[138:139], v[162:163], v[162:163]
	v_add_f32_e32 v94, v137, v94
	v_add_f32_e32 v94, v138, v94
	v_pk_mul_f32 v[140:141], v[96:97], v[96:97]
	v_add_f32_e32 v94, v139, v94
	v_add_f32_e32 v94, v140, v94
	v_pk_mul_f32 v[142:143], v[100:101], v[100:101]
	v_add_f32_e32 v94, v141, v94
	v_add_f32_e32 v94, v142, v94
	v_pk_mul_f32 v[164:165], v[98:99], v[98:99]
	v_add_f32_e32 v94, v143, v94
	v_add_f32_e32 v94, v164, v94
	v_pk_mul_f32 v[166:167], v[102:103], v[102:103]
	v_add_f32_e32 v94, v165, v94
	v_add_f32_e32 v94, v166, v94
	v_pk_mul_f32 v[168:169], v[86:87], v[86:87]
	v_add_f32_e32 v94, v167, v94
	v_add_f32_e32 v94, v168, v94
	v_pk_mul_f32 v[170:171], v[90:91], v[90:91]
	v_add_f32_e32 v94, v169, v94
	v_add_f32_e32 v94, v170, v94
	v_pk_mul_f32 v[172:173], v[88:89], v[88:89]
	v_add_f32_e32 v94, v171, v94
	v_add_f32_e32 v94, v172, v94
	v_pk_mul_f32 v[174:175], v[92:93], v[92:93]
	v_add_f32_e32 v94, v173, v94
	v_add_f32_e32 v94, v174, v94
	v_pk_mul_f32 v[176:177], v[78:79], v[78:79]
	v_add_f32_e32 v94, v175, v94
	v_add_f32_e32 v94, v176, v94
	v_pk_mul_f32 v[178:179], v[82:83], v[82:83]
	v_add_f32_e32 v94, v177, v94
	v_add_f32_e32 v94, v178, v94
	v_pk_mul_f32 v[180:181], v[80:81], v[80:81]
	v_add_f32_e32 v94, v179, v94
	v_add_f32_e32 v94, v180, v94
	v_pk_mul_f32 v[182:183], v[84:85], v[84:85]
	v_add_f32_e32 v94, v181, v94
	v_add_f32_e32 v94, v182, v94
	v_pk_mul_f32 v[184:185], v[70:71], v[70:71]
	v_add_f32_e32 v94, v183, v94
	v_add_f32_e32 v94, v184, v94
	v_pk_mul_f32 v[186:187], v[74:75], v[74:75]
	v_add_f32_e32 v94, v185, v94
	v_add_f32_e32 v94, v186, v94
	v_pk_mul_f32 v[188:189], v[72:73], v[72:73]
	v_add_f32_e32 v94, v187, v94
	v_add_f32_e32 v94, v188, v94
	v_pk_mul_f32 v[190:191], v[76:77], v[76:77]
	v_add_f32_e32 v94, v189, v94
	v_add_f32_e32 v94, v190, v94
	v_pk_mul_f32 v[192:193], v[60:61], v[60:61]
	v_add_f32_e32 v94, v191, v94
	v_add_f32_e32 v94, v192, v94
	v_pk_mul_f32 v[194:195], v[64:65], v[64:65]
	v_add_f32_e32 v94, v193, v94
	v_add_f32_e32 v94, v194, v94
	v_pk_mul_f32 v[196:197], v[62:63], v[62:63]
	v_add_f32_e32 v94, v195, v94
	v_add_f32_e32 v94, v196, v94
	v_pk_mul_f32 v[198:199], v[66:67], v[66:67]
	v_add_f32_e32 v94, v197, v94
	v_add_f32_e32 v94, v199, v94
	v_add_f32_e32 v94, v198, v94
	ds_bpermute_b32 v111, v95, v94
	s_waitcnt lgkmcnt(0)
; __device__ __forceinline__ unsigned pk2(float lo, float hi) { const bf16x2_t v = __builtin_convertvector((f32x2_t){lo, hi}, bf16x2_t); return __builtin_bit_cast(unsigned, v); }
; template <bool FINAL>
; __device__ __forceinline__ void ln_phase(const bf16_t* pre, const float* gam, const float* bet, float* outf, bf16_t* outb, int wave) {
;     ...
;         const float rstd = 1.0f / sqrtf(q * (1.0f / DM) + LN_EPS);
; #pragma unroll
;         for (int j = 0; j < 8; ++j) {
;             const int c0 = 8 * (lane + 64 * j);
;             const f32x4 g0 = *(const f32x4*)(gam + c0), g1 = *(const f32x4*)(gam + c0 + 4), b0 = *(const f32x4*)(bet + c0), b1 = *(const f32x4*)(bet + c0 + 4);
;             const f32x4 y0 = (f32x4){v[j][0], v[j][1], v[j][2], v[j][3]} * rstd * g0 + b0, y1 = (f32x4){v[j][4], v[j][5], v[j][6], v[j][7]} * rstd * g1 + b1;
;             if (FINAL) { float* o = outf + (size_t)row * DM + c0; *(f32x4*)o = y0; *(f32x4*)(o + 4) = y1; }
;             else { u32x4 w; w.x = pk2(y0.x, y0.y); w.y = pk2(y0.z, y0.w); w.z = pk2(y1.x, y1.y); w.w = pk2(y1.z, y1.w); *(u32x4*)(outb + (size_t)row * DM + c0) = w; }
	v_add_f32_e32 v94, v94, v111
	ds_bpermute_b32 v111, v104, v94
	s_waitcnt lgkmcnt(0)
	v_add_f32_e32 v94, v94, v111
	ds_bpermute_b32 v111, v105, v94
	s_waitcnt lgkmcnt(0)
	v_add_f32_e32 v94, v94, v111
	ds_bpermute_b32 v111, v106, v94
	s_waitcnt lgkmcnt(0)
	v_add_f32_e32 v94, v94, v111
	ds_bpermute_b32 v111, v107, v94
	s_waitcnt lgkmcnt(0)
	v_add_f32_e32 v94, v94, v111
	ds_bpermute_b32 v111, v108, v94
	s_waitcnt lgkmcnt(0)
	v_add_f32_e32 v94, v94, v111
	v_fmamk_f32 v94, v94, 0x39800000, v109
	v_mul_f32_e32 v111, 0x4f800000, v94
	v_cmp_gt_f32_e32 vcc, s8, v94
	s_nop 1
	v_cndmask_b32_e32 v94, v94, v111, vcc
	v_sqrt_f32_e32 v111, v94
	s_nop 0
	v_add_u32_e32 v116, -1, v111
	v_add_u32_e32 v117, 1, v111
	v_fma_f32 v118, -v116, v111, v94
	v_fma_f32 v119, -v117, v111, v94
	v_cmp_ge_f32_e64 s[0:1], 0, v118
	s_nop 1
	v_cndmask_b32_e64 v111, v111, v116, s[0:1]
	v_cmp_lt_f32_e64 s[0:1], 0, v119
	s_nop 1
	v_cndmask_b32_e64 v111, v111, v117, s[0:1]
	v_mul_f32_e32 v116, 0x37800000, v111
	v_cndmask_b32_e32 v111, v111, v116, vcc
	v_cmp_class_f32_e32 vcc, v94, v110
	s_nop 1
	v_cndmask_b32_e32 v94, v111, v94, vcc
	v_div_scale_f32 v111, s[0:1], v94, v94, 1.0
	v_rcp_f32_e32 v117, v111
	v_div_scale_f32 v116, vcc, 1.0, v94, 1.0
	v_fma_f32 v118, -v111, v117, 1.0
	v_fmac_f32_e32 v117, v118, v117
	v_mul_f32_e32 v118, v116, v117
	v_fma_f32 v119, -v111, v118, v116
	v_fmac_f32_e32 v118, v119, v117
	v_fma_f32 v111, -v111, v118, v116
	v_div_fmas_f32 v111, v111, v117, v118
	v_div_fixup_f32 v94, v111, v94, 1.0
	v_pk_mul_f32 v[116:117], v[144:145], v[94:95] op_sel_hi:[1,0]
	v_pk_mul_f32 v[118:119], v[146:147], v[94:95] op_sel_hi:[1,0]
	v_pk_mul_f32 v[120:121], v[148:149], v[94:95] op_sel_hi:[1,0]
	v_pk_mul_f32 v[122:123], v[150:151], v[94:95] op_sel_hi:[1,0]
	v_pk_fma_f32 v[6:7], v[6:7], v[118:119], v[14:15]
	v_pk_fma_f32 v[4:5], v[4:5], v[116:117], v[12:13]
	v_pk_fma_f32 v[2:3], v[2:3], v[122:123], v[10:11]
	v_pk_fma_f32 v[0:1], v[0:1], v[120:121], v[8:9]
	global_store_dwordx4 v[68:69], v[4:7], off
	global_store_dwordx4 v[68:69], v[0:3], off offset:16
	global_load_dwordx4 v[0:3], v[26:27], off
	s_nop 0
	global_load_dwordx4 v[4:7], v[24:25], off
	global_load_dwordx4 v[8:11], v[24:25], off offset:16
	global_load_dwordx4 v[12:15], v[26:27], off offset:16
	v_pk_mul_f32 v[116:117], v[154:155], v[94:95] op_sel_hi:[1,0]
	v_pk_mul_f32 v[118:119], v[152:153], v[94:95] op_sel_hi:[1,0]
	v_pk_mul_f32 v[120:121], v[158:159], v[94:95] op_sel_hi:[1,0]
	v_pk_mul_f32 v[122:123], v[156:157], v[94:95] op_sel_hi:[1,0]
	v_pk_mul_f32 v[114:115], v[114:115], v[94:95] op_sel_hi:[1,0]
	v_pk_mul_f32 v[112:113], v[112:113], v[94:95] op_sel_hi:[1,0]
	v_pk_mul_f32 v[100:101], v[100:101], v[94:95] op_sel_hi:[1,0]
	v_pk_mul_f32 v[96:97], v[96:97], v[94:95] op_sel_hi:[1,0]
	v_pk_mul_f32 v[102:103], v[102:103], v[94:95] op_sel_hi:[1,0]
	v_pk_mul_f32 v[98:99], v[98:99], v[94:95] op_sel_hi:[1,0]
	v_pk_mul_f32 v[90:91], v[90:91], v[94:95] op_sel_hi:[1,0]
	v_pk_mul_f32 v[86:87], v[86:87], v[94:95] op_sel_hi:[1,0]
	v_pk_mul_f32 v[92:93], v[92:93], v[94:95] op_sel_hi:[1,0]
	v_pk_mul_f32 v[88:89], v[88:89], v[94:95] op_sel_hi:[1,0]
	v_pk_mul_f32 v[82:83], v[82:83], v[94:95] op_sel_hi:[1,0]
	v_pk_mul_f32 v[78:79], v[78:79], v[94:95] op_sel_hi:[1,0]
	v_pk_mul_f32 v[84:85], v[84:85], v[94:95] op_sel_hi:[1,0]
	v_pk_mul_f32 v[80:81], v[80:81], v[94:95] op_sel_hi:[1,0]
	v_pk_mul_f32 v[74:75], v[74:75], v[94:95] op_sel_hi:[1,0]
	v_pk_mul_f32 v[70:71], v[70:71], v[94:95] op_sel_hi:[1,0]
	v_pk_mul_f32 v[76:77], v[76:77], v[94:95] op_sel_hi:[1,0]
	v_pk_mul_f32 v[72:73], v[72:73], v[94:95] op_sel_hi:[1,0]
	v_pk_mul_f32 v[64:65], v[64:65], v[94:95] op_sel_hi:[1,0]
	v_pk_mul_f32 v[60:61], v[60:61], v[94:95] op_sel_hi:[1,0]
	v_pk_mul_f32 v[66:67], v[66:67], v[94:95] op_sel:[1,0] op_sel_hi:[0,0]
	v_pk_mul_f32 v[62:63], v[62:63], v[94:95] op_sel_hi:[1,0]
	v_pk_fma_f32 v[200:201], v[204:205], v[118:119], v[200:201]
	v_pk_fma_f32 v[202:203], v[206:207], v[116:117], v[202:203]
	v_pk_fma_f32 v[204:205], v[208:209], v[122:123], v[212:213]
	v_pk_fma_f32 v[206:207], v[210:211], v[120:121], v[214:215]
	global_store_dwordx4 v[68:69], v[200:203], off offset:2048
	global_store_dwordx4 v[68:69], v[204:207], off offset:2064
	global_load_dwordx4 v[200:203], v[32:33], off
	s_nop 0
	global_load_dwordx4 v[204:207], v[30:31], off
	global_load_dwordx4 v[208:211], v[30:31], off offset:16
	global_load_dwordx4 v[212:215], v[32:33], off offset:16
	v_pk_mul_f32 v[116:117], v[160:161], v[94:95] op_sel_hi:[1,0]
	v_lshl_add_u64 v[68:69], s[4:5], 0, v[22:23]
	v_pk_mul_f32 v[118:119], v[162:163], v[94:95] op_sel_hi:[1,0]
	s_waitcnt vmcnt(6)
; __device__ __forceinline__ unsigned pk2(float lo, float hi) { const bf16x2_t v = __builtin_convertvector((f32x2_t){lo, hi}, bf16x2_t); return __builtin_bit_cast(unsigned, v); }
; template <bool FINAL>
; __device__ __forceinline__ void ln_phase(const bf16_t* pre, const float* gam, const float* bet, float* outf, bf16_t* outb, int wave) {
;     ...
;         for (int j = 0; j < 8; ++j) {
;             const int c0 = 8 * (lane + 64 * j);
;             const f32x4 g0 = *(const f32x4*)(gam + c0), g1 = *(const f32x4*)(gam + c0 + 4), b0 = *(const f32x4*)(bet + c0), b1 = *(const f32x4*)(bet + c0 + 4);
;             const f32x4 y0 = (f32x4){v[j][0], v[j][1], v[j][2], v[j][3]} * rstd * g0 + b0, y1 = (f32x4){v[j][4], v[j][5], v[j][6], v[j][7]} * rstd * g1 + b1;
;             if (FINAL) { float* o = outf + (size_t)row * DM + c0; *(f32x4*)o = y0; *(f32x4*)(o + 4) = y1; }
;             else { u32x4 w; w.x = pk2(y0.x, y0.y); w.y = pk2(y0.z, y0.w); w.z = pk2(y1.x, y1.y); w.w = pk2(y1.z, y1.w); *(u32x4*)(outb + (size_t)row * DM + c0) = w; }
;         }
	v_pk_fma_f32 v[0:1], v[4:5], v[114:115], v[0:1]
	v_pk_fma_f32 v[2:3], v[6:7], v[116:117], v[2:3]
	v_pk_fma_f32 v[4:5], v[8:9], v[112:113], v[12:13]
	v_pk_fma_f32 v[6:7], v[10:11], v[118:119], v[14:15]
	global_store_dwordx4 v[68:69], v[0:3], off
	global_store_dwordx4 v[68:69], v[4:7], off offset:16
	global_load_dwordx4 v[0:3], v[38:39], off
	s_nop 0
	global_load_dwordx4 v[4:7], v[36:37], off
	global_load_dwordx4 v[8:11], v[36:37], off offset:16
	global_load_dwordx4 v[12:15], v[38:39], off offset:16
	v_lshl_add_u64 v[68:69], s[4:5], 0, v[28:29]
	s_waitcnt vmcnt(6)
	v_pk_fma_f32 v[200:201], v[204:205], v[96:97], v[200:201]
	v_pk_fma_f32 v[202:203], v[206:207], v[100:101], v[202:203]
	v_pk_fma_f32 v[204:205], v[208:209], v[98:99], v[212:213]
	v_pk_fma_f32 v[206:207], v[210:211], v[102:103], v[214:215]
	global_store_dwordx4 v[68:69], v[200:203], off
	global_store_dwordx4 v[68:69], v[204:207], off offset:16
	global_load_dwordx4 v[200:203], v[44:45], off
	s_nop 0
	global_load_dwordx4 v[204:207], v[42:43], off
	global_load_dwordx4 v[208:211], v[42:43], off offset:16
	global_load_dwordx4 v[212:215], v[44:45], off offset:16
	v_lshl_add_u64 v[68:69], s[4:5], 0, v[34:35]
	s_waitcnt vmcnt(6)
	v_pk_fma_f32 v[0:1], v[4:5], v[86:87], v[0:1]
	v_pk_fma_f32 v[2:3], v[6:7], v[90:91], v[2:3]
	v_pk_fma_f32 v[4:5], v[8:9], v[88:89], v[12:13]
	v_pk_fma_f32 v[6:7], v[10:11], v[92:93], v[14:15]
	global_store_dwordx4 v[68:69], v[0:3], off
	global_store_dwordx4 v[68:69], v[4:7], off offset:16
	global_load_dwordx4 v[0:3], v[50:51], off
	s_nop 0
	global_load_dwordx4 v[4:7], v[48:49], off
	global_load_dwordx4 v[8:11], v[48:49], off offset:16
	global_load_dwordx4 v[12:15], v[50:51], off offset:16
	v_lshl_add_u64 v[68:69], s[4:5], 0, v[40:41]
	s_waitcnt vmcnt(6)
	v_pk_fma_f32 v[200:201], v[204:205], v[78:79], v[200:201]
	v_pk_fma_f32 v[202:203], v[206:207], v[82:83], v[202:203]
	v_pk_fma_f32 v[204:205], v[208:209], v[80:81], v[212:213]
	v_pk_fma_f32 v[206:207], v[210:211], v[84:85], v[214:215]
	global_store_dwordx4 v[68:69], v[200:203], off
	global_store_dwordx4 v[68:69], v[204:207], off offset:16
	global_load_dwordx4 v[200:203], v[56:57], off
	s_nop 0
	global_load_dwordx4 v[204:207], v[54:55], off
	global_load_dwordx4 v[208:211], v[54:55], off offset:16
	global_load_dwordx4 v[212:215], v[56:57], off offset:16
	v_lshl_add_u64 v[68:69], s[4:5], 0, v[46:47]
	s_waitcnt vmcnt(6)
	v_pk_fma_f32 v[0:1], v[4:5], v[70:71], v[0:1]
	v_pk_fma_f32 v[2:3], v[6:7], v[74:75], v[2:3]
	v_pk_fma_f32 v[4:5], v[8:9], v[72:73], v[12:13]
	v_pk_fma_f32 v[6:7], v[10:11], v[76:77], v[14:15]
	global_store_dwordx4 v[68:69], v[0:3], off
	global_store_dwordx4 v[68:69], v[4:7], off offset:16
	v_lshl_add_u64 v[68:69], s[4:5], 0, v[52:53]
	s_add_u32 s4, s4, s6
	s_addc_u32 s5, s5, s7
	s_cmpk_lt_i32 s38, 0x2100
	s_waitcnt vmcnt(2)
	v_pk_fma_f32 v[200:201], v[204:205], v[60:61], v[200:201]
	v_pk_fma_f32 v[202:203], v[206:207], v[64:65], v[202:203]
	v_pk_fma_f32 v[204:205], v[208:209], v[62:63], v[212:213]
	v_pk_fma_f32 v[206:207], v[210:211], v[66:67], v[214:215]
	global_store_dwordx4 v[68:69], v[200:203], off
	global_store_dwordx4 v[68:69], v[204:207], off offset:16
	s_cbranch_scc1 .LBB0_1363
